# main GEMM K-loops: MFMA order keeps the B fragment (src0) for four consecutive MFMAs, snake over m
# baseline (speedup 1.0000x reference)
.LBB0_255:
	s_ashr_i32 s15, s14, 31
	s_lshl_b64 s[20:21], s[14:15], 19
	s_add_u32 s42, s31, s20
	s_addc_u32 s43, s34, s21
	s_and_b64 s[20:21], s[4:5], exec
	s_cselect_b32 s15, s43, s53
	s_cselect_b32 s20, s42, s52
	s_ashr_i32 s13, s12, 31
	s_lshl_b64 s[50:51], s[12:13], 19
	s_add_u32 s50, s35, s50
	s_addc_u32 s51, s36, s51
	s_and_b64 s[58:59], s[4:5], exec
	s_cselect_b32 s13, s51, s57
	s_cselect_b32 s21, s50, s56
	s_add_u32 s52, s52, 0x40080
	s_addc_u32 s53, s53, 0
	s_add_u32 s73, s56, 0x100
	s_addc_u32 s75, s57, 0
	s_mov_b32 s82, -2
	s_add_u32 s0, s52, 0xfffc0080
	s_addc_u32 s56, s53, -1
	s_add_i32 s83, 0, 0x10000
	s_cmp_eq_u32 s82, 12
	s_cselect_b32 s59, s15, s56
	s_cselect_b32 s58, s20, s0
	s_cselect_b32 s57, s13, s75
	s_cselect_b32 s56, s21, s73
	s_add_i32 s0, 0, 0x14000
	v_add_u32_e32 v94, s83, v171
	v_add_u32_e32 v155, s0, v171
	ds_read_b128 v[74:77], v94
	ds_read_b128 v[78:81], v94 offset:1024
	ds_read_b128 v[90:93], v94 offset:2048
	ds_read_b128 v[94:97], v94 offset:3072
	ds_read_b128 v[180:183], v155
	ds_read_b128 v[184:187], v155 offset:1024
	ds_read_b128 v[188:191], v155 offset:2048
	ds_read_b128 v[192:195], v155 offset:3072
	v_lshl_add_u64 v[168:169], s[52:53], 0, v[164:165]
	s_add_i32 m0, s61, 0xc000
	ds_read_b128 v[196:199], v177
	ds_read_b128 v[200:203], v177 offset:1024
	ds_read_b128 v[204:207], v177 offset:2048
	ds_read_b128 v[208:211], v177 offset:3072
	ds_read_b128 v[212:215], v177 offset:4096
	ds_read_b128 v[216:219], v177 offset:5120
	ds_read_b128 v[230:233], v177 offset:6144
	ds_read_b128 v[238:241], v177 offset:7168
	global_load_lds_dwordx4 v[168:169], off
	v_lshl_add_u64 v[168:169], s[52:53], 0, v[166:167]
	s_add_i32 m0, s61, 0xe000
	s_nop 0
	global_load_lds_dwordx4 v[168:169], off
	s_waitcnt vmcnt(8)
	s_waitcnt lgkmcnt(0)
	s_barrier
	s_setprio 1
	s_waitcnt lgkmcnt(0)
	v_mfma_f32_16x16x32_bf16 v[142:145], v[74:77], v[196:199], 0
	v_mfma_f32_16x16x32_bf16 v[126:129], v[74:77], v[204:207], 0
	v_mfma_f32_16x16x32_bf16 v[110:113], v[74:77], v[212:215], 0
	v_mfma_f32_16x16x32_bf16 v[86:89], v[74:77], v[230:233], 0
	v_mfma_f32_16x16x32_bf16 v[70:73], v[90:93], v[230:233], 0
	v_mfma_f32_16x16x32_bf16 v[102:105], v[90:93], v[212:215], 0
	v_mfma_f32_16x16x32_bf16 v[118:121], v[90:93], v[204:207], 0
	v_mfma_f32_16x16x32_bf16 v[134:137], v[90:93], v[196:199], 0
	v_mfma_f32_16x16x32_bf16 v[142:145], v[78:81], v[200:203], v[142:145]
	v_mfma_f32_16x16x32_bf16 v[126:129], v[78:81], v[208:211], v[126:129]
	v_mfma_f32_16x16x32_bf16 v[110:113], v[78:81], v[216:219], v[110:113]
	v_mfma_f32_16x16x32_bf16 v[86:89], v[78:81], v[238:241], v[86:89]
	v_mfma_f32_16x16x32_bf16 v[70:73], v[94:97], v[238:241], v[70:73]
	v_mfma_f32_16x16x32_bf16 v[102:105], v[94:97], v[216:219], v[102:105]
	v_mfma_f32_16x16x32_bf16 v[118:121], v[94:97], v[208:211], v[118:121]
	v_mfma_f32_16x16x32_bf16 v[134:137], v[94:97], v[200:203], v[134:137]
	s_setprio 0
	s_setprio 1
	v_mfma_f32_16x16x32_bf16 v[138:141], v[180:183], v[196:199], 0
	v_mfma_f32_16x16x32_bf16 v[122:125], v[180:183], v[204:207], 0
	v_mfma_f32_16x16x32_bf16 v[106:109], v[180:183], v[212:215], 0
	v_mfma_f32_16x16x32_bf16 v[82:85], v[180:183], v[230:233], 0
	v_mfma_f32_16x16x32_bf16 v[66:69], v[188:191], v[230:233], 0
	v_mfma_f32_16x16x32_bf16 v[98:101], v[188:191], v[212:215], 0
	v_mfma_f32_16x16x32_bf16 v[114:117], v[188:191], v[204:207], 0
	v_mfma_f32_16x16x32_bf16 v[130:133], v[188:191], v[196:199], 0
	v_mfma_f32_16x16x32_bf16 v[138:141], v[184:187], v[200:203], v[138:141]
	v_mfma_f32_16x16x32_bf16 v[122:125], v[184:187], v[208:211], v[122:125]
	v_mfma_f32_16x16x32_bf16 v[106:109], v[184:187], v[216:219], v[106:109]
	v_mfma_f32_16x16x32_bf16 v[82:85], v[184:187], v[238:241], v[82:85]
	v_mfma_f32_16x16x32_bf16 v[66:69], v[192:195], v[238:241], v[66:69]
	v_mfma_f32_16x16x32_bf16 v[98:101], v[192:195], v[216:219], v[98:101]
	v_mfma_f32_16x16x32_bf16 v[114:117], v[192:195], v[208:211], v[114:117]
	v_mfma_f32_16x16x32_bf16 v[130:133], v[192:195], v[200:203], v[130:133]
	s_setprio 0
	s_barrier
	s_add_i32 s83, s83, s37
	v_lshl_add_u64 v[168:169], s[56:57], 0, v[150:151]
	s_mov_b32 m0, s83
	ds_read_b128 v[196:199], v177 offset:16384
	ds_read_b128 v[200:203], v177 offset:17408
	ds_read_b128 v[204:207], v177 offset:18432
	ds_read_b128 v[208:211], v177 offset:19456
	ds_read_b128 v[212:215], v177 offset:20480
	ds_read_b128 v[216:219], v177 offset:21504
	ds_read_b128 v[230:233], v177 offset:22528
	ds_read_b128 v[238:241], v177 offset:23552
	global_load_lds_dwordx4 v[168:169], off
	s_add_i32 m0, s83, 0x2000
	s_add_u32 s84, s56, 0x40000
	v_lshl_add_u64 v[242:243], s[56:57], 0, v[146:147]
	s_addc_u32 s85, s57, 0
	s_add_i32 s0, s0, s37
	global_load_lds_dwordx4 v[242:243], off
	v_lshl_add_u64 v[244:245], s[84:85], 0, v[150:151]
	s_mov_b32 m0, s0
	v_lshl_add_u64 v[246:247], s[58:59], 0, v[148:149]
	global_load_lds_dwordx4 v[244:245], off
	v_lshl_add_u64 v[244:245], s[84:85], 0, v[146:147]
	s_add_i32 m0, s0, 0x2000
	s_nop 0
	global_load_lds_dwordx4 v[244:245], off
	v_lshl_add_u64 v[244:245], s[58:59], 0, v[152:153]
	s_mov_b32 m0, s61
	s_nop 0
	global_load_lds_dwordx4 v[244:245], off
	s_mov_b32 m0, s64
	s_nop 0
	global_load_lds_dwordx4 v[246:247], off
	s_waitcnt vmcnt(8)
	s_waitcnt lgkmcnt(0)
	s_barrier
	s_setprio 1
	s_waitcnt lgkmcnt(0)
	v_mfma_f32_16x16x32_bf16 v[62:65], v[74:77], v[196:199], 0
	v_mfma_f32_16x16x32_bf16 v[46:49], v[74:77], v[204:207], 0
	v_mfma_f32_16x16x32_bf16 v[30:33], v[74:77], v[212:215], 0
	v_mfma_f32_16x16x32_bf16 v[14:17], v[74:77], v[230:233], 0
	v_mfma_f32_16x16x32_bf16 v[6:9], v[90:93], v[230:233], 0
	v_mfma_f32_16x16x32_bf16 v[22:25], v[90:93], v[212:215], 0
	v_mfma_f32_16x16x32_bf16 v[38:41], v[90:93], v[204:207], 0
	v_mfma_f32_16x16x32_bf16 v[54:57], v[90:93], v[196:199], 0
	v_mfma_f32_16x16x32_bf16 v[62:65], v[78:81], v[200:203], v[62:65]
	v_mfma_f32_16x16x32_bf16 v[46:49], v[78:81], v[208:211], v[46:49]
	v_mfma_f32_16x16x32_bf16 v[30:33], v[78:81], v[216:219], v[30:33]
	v_mfma_f32_16x16x32_bf16 v[14:17], v[78:81], v[238:241], v[14:17]
	v_mfma_f32_16x16x32_bf16 v[6:9], v[94:97], v[238:241], v[6:9]
	v_mfma_f32_16x16x32_bf16 v[22:25], v[94:97], v[216:219], v[22:25]
	v_mfma_f32_16x16x32_bf16 v[38:41], v[94:97], v[208:211], v[38:41]
	v_mfma_f32_16x16x32_bf16 v[54:57], v[94:97], v[200:203], v[54:57]
	s_setprio 0
	s_setprio 1
	v_mfma_f32_16x16x32_bf16 v[58:61], v[180:183], v[196:199], 0
	v_mfma_f32_16x16x32_bf16 v[42:45], v[180:183], v[204:207], 0
	v_mfma_f32_16x16x32_bf16 v[26:29], v[180:183], v[212:215], 0
	v_mfma_f32_16x16x32_bf16 v[10:13], v[180:183], v[230:233], 0
	v_mfma_f32_16x16x32_bf16 v[2:5], v[188:191], v[230:233], 0
	v_mfma_f32_16x16x32_bf16 v[18:21], v[188:191], v[212:215], 0
	v_mfma_f32_16x16x32_bf16 v[34:37], v[188:191], v[204:207], 0
	v_mfma_f32_16x16x32_bf16 v[50:53], v[188:191], v[196:199], 0
	v_mfma_f32_16x16x32_bf16 v[58:61], v[184:187], v[200:203], v[58:61]
	v_mfma_f32_16x16x32_bf16 v[42:45], v[184:187], v[208:211], v[42:45]
	v_mfma_f32_16x16x32_bf16 v[26:29], v[184:187], v[216:219], v[26:29]
	v_mfma_f32_16x16x32_bf16 v[10:13], v[184:187], v[238:241], v[10:13]
	v_mfma_f32_16x16x32_bf16 v[2:5], v[192:195], v[238:241], v[2:5]
	v_mfma_f32_16x16x32_bf16 v[18:21], v[192:195], v[216:219], v[18:21]
	v_mfma_f32_16x16x32_bf16 v[34:37], v[192:195], v[208:211], v[34:37]
	v_mfma_f32_16x16x32_bf16 v[50:53], v[192:195], v[200:203], v[50:53]
	s_setprio 0
	s_barrier
	s_add_i32 s0, 0, 0x18000
	s_add_i32 s83, 0, 0x1c000
	v_add_u32_e32 v94, s0, v171
	v_add_u32_e32 v155, s83, v171
	ds_read_b128 v[74:77], v94
	ds_read_b128 v[78:81], v94 offset:1024
	ds_read_b128 v[90:93], v94 offset:2048
	ds_read_b128 v[94:97], v94 offset:3072
	ds_read_b128 v[180:183], v155
	ds_read_b128 v[184:187], v155 offset:1024
	ds_read_b128 v[188:191], v155 offset:2048
	ds_read_b128 v[192:195], v155 offset:3072
	s_add_u32 s58, s58, 0x40000
	s_addc_u32 s59, s59, 0
	s_mov_b32 m0, s65
	v_lshl_add_u64 v[248:249], s[58:59], 0, v[152:153]
	ds_read_b128 v[196:199], v177 offset:32768
	ds_read_b128 v[200:203], v177 offset:33792
	ds_read_b128 v[204:207], v177 offset:34816
	ds_read_b128 v[208:211], v177 offset:35840
	ds_read_b128 v[212:215], v177 offset:36864
	ds_read_b128 v[216:219], v177 offset:37888
	ds_read_b128 v[230:233], v177 offset:38912
	ds_read_b128 v[238:241], v177 offset:39936
	global_load_lds_dwordx4 v[248:249], off
	v_lshl_add_u64 v[248:249], s[58:59], 0, v[148:149]
	s_mov_b32 m0, s66
	s_nop 0
	global_load_lds_dwordx4 v[248:249], off
	s_waitcnt vmcnt(8)
	s_waitcnt lgkmcnt(0)
	s_barrier
	s_setprio 1
	s_waitcnt lgkmcnt(0)
	v_mfma_f32_16x16x32_bf16 v[142:145], v[74:77], v[196:199], v[142:145]
	v_mfma_f32_16x16x32_bf16 v[126:129], v[74:77], v[204:207], v[126:129]
	v_mfma_f32_16x16x32_bf16 v[110:113], v[74:77], v[212:215], v[110:113]
	v_mfma_f32_16x16x32_bf16 v[86:89], v[74:77], v[230:233], v[86:89]
	v_mfma_f32_16x16x32_bf16 v[70:73], v[90:93], v[230:233], v[70:73]
	v_mfma_f32_16x16x32_bf16 v[102:105], v[90:93], v[212:215], v[102:105]
	v_mfma_f32_16x16x32_bf16 v[118:121], v[90:93], v[204:207], v[118:121]
	v_mfma_f32_16x16x32_bf16 v[134:137], v[90:93], v[196:199], v[134:137]
	v_mfma_f32_16x16x32_bf16 v[142:145], v[78:81], v[200:203], v[142:145]
	v_mfma_f32_16x16x32_bf16 v[126:129], v[78:81], v[208:211], v[126:129]
	v_mfma_f32_16x16x32_bf16 v[110:113], v[78:81], v[216:219], v[110:113]
	v_mfma_f32_16x16x32_bf16 v[86:89], v[78:81], v[238:241], v[86:89]
	v_mfma_f32_16x16x32_bf16 v[70:73], v[94:97], v[238:241], v[70:73]
	v_mfma_f32_16x16x32_bf16 v[102:105], v[94:97], v[216:219], v[102:105]
	v_mfma_f32_16x16x32_bf16 v[118:121], v[94:97], v[208:211], v[118:121]
	v_mfma_f32_16x16x32_bf16 v[134:137], v[94:97], v[200:203], v[134:137]
	s_setprio 0
	s_setprio 1
	v_mfma_f32_16x16x32_bf16 v[138:141], v[180:183], v[196:199], v[138:141]
	v_mfma_f32_16x16x32_bf16 v[122:125], v[180:183], v[204:207], v[122:125]
	v_mfma_f32_16x16x32_bf16 v[106:109], v[180:183], v[212:215], v[106:109]
	v_mfma_f32_16x16x32_bf16 v[82:85], v[180:183], v[230:233], v[82:85]
	v_mfma_f32_16x16x32_bf16 v[66:69], v[188:191], v[230:233], v[66:69]
	v_mfma_f32_16x16x32_bf16 v[98:101], v[188:191], v[212:215], v[98:101]
	v_mfma_f32_16x16x32_bf16 v[114:117], v[188:191], v[204:207], v[114:117]
	v_mfma_f32_16x16x32_bf16 v[130:133], v[188:191], v[196:199], v[130:133]
	v_mfma_f32_16x16x32_bf16 v[138:141], v[184:187], v[200:203], v[138:141]
	v_mfma_f32_16x16x32_bf16 v[122:125], v[184:187], v[208:211], v[122:125]
	v_mfma_f32_16x16x32_bf16 v[106:109], v[184:187], v[216:219], v[106:109]
	v_mfma_f32_16x16x32_bf16 v[82:85], v[184:187], v[238:241], v[82:85]
	v_mfma_f32_16x16x32_bf16 v[66:69], v[192:195], v[238:241], v[66:69]
	v_mfma_f32_16x16x32_bf16 v[98:101], v[192:195], v[216:219], v[98:101]
	v_mfma_f32_16x16x32_bf16 v[114:117], v[192:195], v[208:211], v[114:117]
	v_mfma_f32_16x16x32_bf16 v[130:133], v[192:195], v[200:203], v[130:133]
	s_setprio 0
	s_barrier
	s_add_i32 s0, s0, s37
	v_lshl_add_u64 v[168:169], v[168:169], 0, s[76:77]
	s_mov_b32 m0, s0
	ds_read_b128 v[196:199], v177 offset:49152
	ds_read_b128 v[200:203], v177 offset:50176
	ds_read_b128 v[204:207], v177 offset:51200
	ds_read_b128 v[208:211], v177 offset:52224
	ds_read_b128 v[212:215], v177 offset:53248
	ds_read_b128 v[216:219], v177 offset:54272
	ds_read_b128 v[230:233], v177 offset:55296
	ds_read_b128 v[238:241], v177 offset:56320
	global_load_lds_dwordx4 v[168:169], off
	s_add_i32 m0, s0, 0x2000
	s_add_u32 s56, s56, 0x40080
	v_lshl_add_u64 v[168:169], v[242:243], 0, s[76:77]
	s_addc_u32 s57, s57, 0
	s_add_i32 s0, s83, s37
	global_load_lds_dwordx4 v[168:169], off
	v_lshl_add_u64 v[168:169], s[56:57], 0, v[150:151]
	s_mov_b32 m0, s0
	s_nop 0
	global_load_lds_dwordx4 v[168:169], off
	v_lshl_add_u64 v[168:169], s[56:57], 0, v[146:147]
	s_add_i32 m0, s0, 0x2000
	s_nop 0
	global_load_lds_dwordx4 v[168:169], off
	v_lshl_add_u64 v[168:169], v[244:245], 0, s[76:77]
	s_mov_b32 m0, s67
	s_nop 0
	global_load_lds_dwordx4 v[168:169], off
	v_lshl_add_u64 v[168:169], v[246:247], 0, s[76:77]
	s_mov_b32 m0, s68
	s_nop 0
	global_load_lds_dwordx4 v[168:169], off
	s_waitcnt vmcnt(8)
	s_waitcnt lgkmcnt(0)
	s_barrier
	s_setprio 1
	s_waitcnt lgkmcnt(0)
	v_mfma_f32_16x16x32_bf16 v[62:65], v[74:77], v[196:199], v[62:65]
	v_mfma_f32_16x16x32_bf16 v[46:49], v[74:77], v[204:207], v[46:49]
	v_mfma_f32_16x16x32_bf16 v[30:33], v[74:77], v[212:215], v[30:33]
	v_mfma_f32_16x16x32_bf16 v[14:17], v[74:77], v[230:233], v[14:17]
	v_mfma_f32_16x16x32_bf16 v[6:9], v[90:93], v[230:233], v[6:9]
	v_mfma_f32_16x16x32_bf16 v[22:25], v[90:93], v[212:215], v[22:25]
	v_mfma_f32_16x16x32_bf16 v[38:41], v[90:93], v[204:207], v[38:41]
	v_mfma_f32_16x16x32_bf16 v[54:57], v[90:93], v[196:199], v[54:57]
	v_mfma_f32_16x16x32_bf16 v[62:65], v[78:81], v[200:203], v[62:65]
	v_mfma_f32_16x16x32_bf16 v[46:49], v[78:81], v[208:211], v[46:49]
	v_mfma_f32_16x16x32_bf16 v[30:33], v[78:81], v[216:219], v[30:33]
	v_mfma_f32_16x16x32_bf16 v[14:17], v[78:81], v[238:241], v[14:17]
	v_mfma_f32_16x16x32_bf16 v[6:9], v[94:97], v[238:241], v[6:9]
	v_mfma_f32_16x16x32_bf16 v[22:25], v[94:97], v[216:219], v[22:25]
	v_mfma_f32_16x16x32_bf16 v[38:41], v[94:97], v[208:211], v[38:41]
	v_mfma_f32_16x16x32_bf16 v[54:57], v[94:97], v[200:203], v[54:57]
	s_setprio 0
	s_setprio 1
	v_mfma_f32_16x16x32_bf16 v[58:61], v[180:183], v[196:199], v[58:61]
	v_mfma_f32_16x16x32_bf16 v[42:45], v[180:183], v[204:207], v[42:45]
	v_mfma_f32_16x16x32_bf16 v[26:29], v[180:183], v[212:215], v[26:29]
	v_mfma_f32_16x16x32_bf16 v[10:13], v[180:183], v[230:233], v[10:13]
	v_mfma_f32_16x16x32_bf16 v[2:5], v[188:191], v[230:233], v[2:5]
	v_mfma_f32_16x16x32_bf16 v[18:21], v[188:191], v[212:215], v[18:21]
	v_mfma_f32_16x16x32_bf16 v[34:37], v[188:191], v[204:207], v[34:37]
	v_mfma_f32_16x16x32_bf16 v[50:53], v[188:191], v[196:199], v[50:53]
	v_mfma_f32_16x16x32_bf16 v[58:61], v[184:187], v[200:203], v[58:61]
	v_mfma_f32_16x16x32_bf16 v[42:45], v[184:187], v[208:211], v[42:45]
	v_mfma_f32_16x16x32_bf16 v[26:29], v[184:187], v[216:219], v[26:29]
	v_mfma_f32_16x16x32_bf16 v[10:13], v[184:187], v[238:241], v[10:13]
	v_mfma_f32_16x16x32_bf16 v[2:5], v[192:195], v[238:241], v[2:5]
	v_mfma_f32_16x16x32_bf16 v[18:21], v[192:195], v[216:219], v[18:21]
	v_mfma_f32_16x16x32_bf16 v[34:37], v[192:195], v[208:211], v[34:37]
	v_mfma_f32_16x16x32_bf16 v[50:53], v[192:195], v[200:203], v[50:53]
	s_setprio 0
	s_barrier
	s_add_i32 s82, s82, 2
	s_add_u32 s52, s52, 0x100
	s_addc_u32 s53, s53, 0
	s_add_u32 s73, s73, 0x100
	s_addc_u32 s75, s75, 0
.LBB0_256:
	s_add_u32 s0, s52, 0xfffc0080
	s_addc_u32 s56, s53, -1
	s_add_i32 s83, 0, 0x10000
	s_cmp_eq_u32 s82, 12
	s_cselect_b32 s59, s15, s56
	s_cselect_b32 s58, s20, s0
	s_cselect_b32 s57, s13, s75
	s_cselect_b32 s56, s21, s73
	s_add_i32 s0, 0, 0x14000
	v_add_u32_e32 v94, s83, v171
	v_add_u32_e32 v155, s0, v171
	ds_read_b128 v[74:77], v94
	ds_read_b128 v[78:81], v94 offset:1024
	ds_read_b128 v[90:93], v94 offset:2048
	ds_read_b128 v[94:97], v94 offset:3072
	ds_read_b128 v[180:183], v155
	ds_read_b128 v[184:187], v155 offset:1024
	ds_read_b128 v[188:191], v155 offset:2048
	ds_read_b128 v[192:195], v155 offset:3072
	v_lshl_add_u64 v[168:169], s[52:53], 0, v[164:165]
	s_add_i32 m0, s61, 0xc000
	ds_read_b128 v[196:199], v177
	ds_read_b128 v[200:203], v177 offset:1024
	ds_read_b128 v[204:207], v177 offset:2048
	ds_read_b128 v[208:211], v177 offset:3072
	ds_read_b128 v[212:215], v177 offset:4096
	ds_read_b128 v[216:219], v177 offset:5120
	ds_read_b128 v[230:233], v177 offset:6144
	ds_read_b128 v[238:241], v177 offset:7168
	global_load_lds_dwordx4 v[168:169], off
	v_lshl_add_u64 v[168:169], s[52:53], 0, v[166:167]
	s_add_i32 m0, s61, 0xe000
	s_nop 0
	global_load_lds_dwordx4 v[168:169], off
	s_waitcnt vmcnt(8)
	s_waitcnt lgkmcnt(0)
	s_barrier
	s_setprio 1
	s_waitcnt lgkmcnt(0)
	v_mfma_f32_16x16x32_bf16 v[142:145], v[74:77], v[196:199], v[142:145]
	v_mfma_f32_16x16x32_bf16 v[126:129], v[74:77], v[204:207], v[126:129]
	v_mfma_f32_16x16x32_bf16 v[110:113], v[74:77], v[212:215], v[110:113]
	v_mfma_f32_16x16x32_bf16 v[86:89], v[74:77], v[230:233], v[86:89]
	v_mfma_f32_16x16x32_bf16 v[70:73], v[90:93], v[230:233], v[70:73]
	v_mfma_f32_16x16x32_bf16 v[102:105], v[90:93], v[212:215], v[102:105]
	v_mfma_f32_16x16x32_bf16 v[118:121], v[90:93], v[204:207], v[118:121]
	v_mfma_f32_16x16x32_bf16 v[134:137], v[90:93], v[196:199], v[134:137]
	v_mfma_f32_16x16x32_bf16 v[142:145], v[78:81], v[200:203], v[142:145]
	v_mfma_f32_16x16x32_bf16 v[126:129], v[78:81], v[208:211], v[126:129]
	v_mfma_f32_16x16x32_bf16 v[110:113], v[78:81], v[216:219], v[110:113]
	v_mfma_f32_16x16x32_bf16 v[86:89], v[78:81], v[238:241], v[86:89]
	v_mfma_f32_16x16x32_bf16 v[70:73], v[94:97], v[238:241], v[70:73]
	v_mfma_f32_16x16x32_bf16 v[102:105], v[94:97], v[216:219], v[102:105]
	v_mfma_f32_16x16x32_bf16 v[118:121], v[94:97], v[208:211], v[118:121]
	v_mfma_f32_16x16x32_bf16 v[134:137], v[94:97], v[200:203], v[134:137]
	s_setprio 0
	s_setprio 1
	v_mfma_f32_16x16x32_bf16 v[138:141], v[180:183], v[196:199], v[138:141]
	v_mfma_f32_16x16x32_bf16 v[122:125], v[180:183], v[204:207], v[122:125]
	v_mfma_f32_16x16x32_bf16 v[106:109], v[180:183], v[212:215], v[106:109]
	v_mfma_f32_16x16x32_bf16 v[82:85], v[180:183], v[230:233], v[82:85]
	v_mfma_f32_16x16x32_bf16 v[66:69], v[188:191], v[230:233], v[66:69]
	v_mfma_f32_16x16x32_bf16 v[98:101], v[188:191], v[212:215], v[98:101]
	v_mfma_f32_16x16x32_bf16 v[114:117], v[188:191], v[204:207], v[114:117]
	v_mfma_f32_16x16x32_bf16 v[130:133], v[188:191], v[196:199], v[130:133]
	v_mfma_f32_16x16x32_bf16 v[138:141], v[184:187], v[200:203], v[138:141]
	v_mfma_f32_16x16x32_bf16 v[122:125], v[184:187], v[208:211], v[122:125]
	v_mfma_f32_16x16x32_bf16 v[106:109], v[184:187], v[216:219], v[106:109]
	v_mfma_f32_16x16x32_bf16 v[82:85], v[184:187], v[238:241], v[82:85]
	v_mfma_f32_16x16x32_bf16 v[66:69], v[192:195], v[238:241], v[66:69]
	v_mfma_f32_16x16x32_bf16 v[98:101], v[192:195], v[216:219], v[98:101]
	v_mfma_f32_16x16x32_bf16 v[114:117], v[192:195], v[208:211], v[114:117]
	v_mfma_f32_16x16x32_bf16 v[130:133], v[192:195], v[200:203], v[130:133]
	s_setprio 0
	s_barrier
	s_add_i32 s83, s83, s37
	v_lshl_add_u64 v[168:169], s[56:57], 0, v[150:151]
	s_mov_b32 m0, s83
	ds_read_b128 v[196:199], v177 offset:16384
	ds_read_b128 v[200:203], v177 offset:17408
	ds_read_b128 v[204:207], v177 offset:18432
	ds_read_b128 v[208:211], v177 offset:19456
	ds_read_b128 v[212:215], v177 offset:20480
	ds_read_b128 v[216:219], v177 offset:21504
	ds_read_b128 v[230:233], v177 offset:22528
	ds_read_b128 v[238:241], v177 offset:23552
	global_load_lds_dwordx4 v[168:169], off
	s_add_i32 m0, s83, 0x2000
	s_add_u32 s84, s56, 0x40000
	v_lshl_add_u64 v[242:243], s[56:57], 0, v[146:147]
	s_addc_u32 s85, s57, 0
	s_add_i32 s0, s0, s37
	global_load_lds_dwordx4 v[242:243], off
	v_lshl_add_u64 v[244:245], s[84:85], 0, v[150:151]
	s_mov_b32 m0, s0
	v_lshl_add_u64 v[246:247], s[58:59], 0, v[148:149]
	global_load_lds_dwordx4 v[244:245], off
	v_lshl_add_u64 v[244:245], s[84:85], 0, v[146:147]
	s_add_i32 m0, s0, 0x2000
	s_nop 0
	global_load_lds_dwordx4 v[244:245], off
	v_lshl_add_u64 v[244:245], s[58:59], 0, v[152:153]
	s_mov_b32 m0, s61
	s_nop 0
	global_load_lds_dwordx4 v[244:245], off
	s_mov_b32 m0, s64
	s_nop 0
	global_load_lds_dwordx4 v[246:247], off
	s_waitcnt vmcnt(8)
	s_waitcnt lgkmcnt(0)
	s_barrier
	s_setprio 1
	s_waitcnt lgkmcnt(0)
	v_mfma_f32_16x16x32_bf16 v[62:65], v[74:77], v[196:199], v[62:65]
	v_mfma_f32_16x16x32_bf16 v[46:49], v[74:77], v[204:207], v[46:49]
	v_mfma_f32_16x16x32_bf16 v[30:33], v[74:77], v[212:215], v[30:33]
	v_mfma_f32_16x16x32_bf16 v[14:17], v[74:77], v[230:233], v[14:17]
	v_mfma_f32_16x16x32_bf16 v[6:9], v[90:93], v[230:233], v[6:9]
	v_mfma_f32_16x16x32_bf16 v[22:25], v[90:93], v[212:215], v[22:25]
	v_mfma_f32_16x16x32_bf16 v[38:41], v[90:93], v[204:207], v[38:41]
	v_mfma_f32_16x16x32_bf16 v[54:57], v[90:93], v[196:199], v[54:57]
	v_mfma_f32_16x16x32_bf16 v[62:65], v[78:81], v[200:203], v[62:65]
	v_mfma_f32_16x16x32_bf16 v[46:49], v[78:81], v[208:211], v[46:49]
	v_mfma_f32_16x16x32_bf16 v[30:33], v[78:81], v[216:219], v[30:33]
	v_mfma_f32_16x16x32_bf16 v[14:17], v[78:81], v[238:241], v[14:17]
	v_mfma_f32_16x16x32_bf16 v[6:9], v[94:97], v[238:241], v[6:9]
	v_mfma_f32_16x16x32_bf16 v[22:25], v[94:97], v[216:219], v[22:25]
	v_mfma_f32_16x16x32_bf16 v[38:41], v[94:97], v[208:211], v[38:41]
	v_mfma_f32_16x16x32_bf16 v[54:57], v[94:97], v[200:203], v[54:57]
	s_setprio 0
	s_setprio 1
	v_mfma_f32_16x16x32_bf16 v[58:61], v[180:183], v[196:199], v[58:61]
	v_mfma_f32_16x16x32_bf16 v[42:45], v[180:183], v[204:207], v[42:45]
	v_mfma_f32_16x16x32_bf16 v[26:29], v[180:183], v[212:215], v[26:29]
	v_mfma_f32_16x16x32_bf16 v[10:13], v[180:183], v[230:233], v[10:13]
	v_mfma_f32_16x16x32_bf16 v[2:5], v[188:191], v[230:233], v[2:5]
	v_mfma_f32_16x16x32_bf16 v[18:21], v[188:191], v[212:215], v[18:21]
	v_mfma_f32_16x16x32_bf16 v[34:37], v[188:191], v[204:207], v[34:37]
	v_mfma_f32_16x16x32_bf16 v[50:53], v[188:191], v[196:199], v[50:53]
	v_mfma_f32_16x16x32_bf16 v[58:61], v[184:187], v[200:203], v[58:61]
	v_mfma_f32_16x16x32_bf16 v[42:45], v[184:187], v[208:211], v[42:45]
	v_mfma_f32_16x16x32_bf16 v[26:29], v[184:187], v[216:219], v[26:29]
	v_mfma_f32_16x16x32_bf16 v[10:13], v[184:187], v[238:241], v[10:13]
	v_mfma_f32_16x16x32_bf16 v[2:5], v[192:195], v[238:241], v[2:5]
	v_mfma_f32_16x16x32_bf16 v[18:21], v[192:195], v[216:219], v[18:21]
	v_mfma_f32_16x16x32_bf16 v[34:37], v[192:195], v[208:211], v[34:37]
	v_mfma_f32_16x16x32_bf16 v[50:53], v[192:195], v[200:203], v[50:53]
	s_setprio 0
	s_barrier
	s_add_i32 s0, 0, 0x18000
	s_add_i32 s83, 0, 0x1c000
	v_add_u32_e32 v94, s0, v171
	v_add_u32_e32 v155, s83, v171
	ds_read_b128 v[74:77], v94
	ds_read_b128 v[78:81], v94 offset:1024
	ds_read_b128 v[90:93], v94 offset:2048
	ds_read_b128 v[94:97], v94 offset:3072
	ds_read_b128 v[180:183], v155
	ds_read_b128 v[184:187], v155 offset:1024
	ds_read_b128 v[188:191], v155 offset:2048
	ds_read_b128 v[192:195], v155 offset:3072
	s_add_u32 s58, s58, 0x40000
	s_addc_u32 s59, s59, 0
	s_mov_b32 m0, s65
	v_lshl_add_u64 v[248:249], s[58:59], 0, v[152:153]
	ds_read_b128 v[196:199], v177 offset:32768
	ds_read_b128 v[200:203], v177 offset:33792
	ds_read_b128 v[204:207], v177 offset:34816
	ds_read_b128 v[208:211], v177 offset:35840
	ds_read_b128 v[212:215], v177 offset:36864
	ds_read_b128 v[216:219], v177 offset:37888
	ds_read_b128 v[230:233], v177 offset:38912
	ds_read_b128 v[238:241], v177 offset:39936
	global_load_lds_dwordx4 v[248:249], off
	v_lshl_add_u64 v[248:249], s[58:59], 0, v[148:149]
	s_mov_b32 m0, s66
	s_nop 0
	global_load_lds_dwordx4 v[248:249], off
	s_waitcnt vmcnt(8)
	s_waitcnt lgkmcnt(0)
	s_barrier
	s_setprio 1
	s_waitcnt lgkmcnt(0)
	v_mfma_f32_16x16x32_bf16 v[142:145], v[74:77], v[196:199], v[142:145]
	v_mfma_f32_16x16x32_bf16 v[126:129], v[74:77], v[204:207], v[126:129]
	v_mfma_f32_16x16x32_bf16 v[110:113], v[74:77], v[212:215], v[110:113]
	v_mfma_f32_16x16x32_bf16 v[86:89], v[74:77], v[230:233], v[86:89]
	v_mfma_f32_16x16x32_bf16 v[70:73], v[90:93], v[230:233], v[70:73]
	v_mfma_f32_16x16x32_bf16 v[102:105], v[90:93], v[212:215], v[102:105]
	v_mfma_f32_16x16x32_bf16 v[118:121], v[90:93], v[204:207], v[118:121]
	v_mfma_f32_16x16x32_bf16 v[134:137], v[90:93], v[196:199], v[134:137]
	v_mfma_f32_16x16x32_bf16 v[142:145], v[78:81], v[200:203], v[142:145]
	v_mfma_f32_16x16x32_bf16 v[126:129], v[78:81], v[208:211], v[126:129]
	v_mfma_f32_16x16x32_bf16 v[110:113], v[78:81], v[216:219], v[110:113]
	v_mfma_f32_16x16x32_bf16 v[86:89], v[78:81], v[238:241], v[86:89]
	v_mfma_f32_16x16x32_bf16 v[70:73], v[94:97], v[238:241], v[70:73]
	v_mfma_f32_16x16x32_bf16 v[102:105], v[94:97], v[216:219], v[102:105]
	v_mfma_f32_16x16x32_bf16 v[118:121], v[94:97], v[208:211], v[118:121]
	v_mfma_f32_16x16x32_bf16 v[134:137], v[94:97], v[200:203], v[134:137]
	s_setprio 0
	s_setprio 1
	v_mfma_f32_16x16x32_bf16 v[138:141], v[180:183], v[196:199], v[138:141]
	v_mfma_f32_16x16x32_bf16 v[122:125], v[180:183], v[204:207], v[122:125]
	v_mfma_f32_16x16x32_bf16 v[106:109], v[180:183], v[212:215], v[106:109]
	v_mfma_f32_16x16x32_bf16 v[82:85], v[180:183], v[230:233], v[82:85]
	v_mfma_f32_16x16x32_bf16 v[66:69], v[188:191], v[230:233], v[66:69]
	v_mfma_f32_16x16x32_bf16 v[98:101], v[188:191], v[212:215], v[98:101]
	v_mfma_f32_16x16x32_bf16 v[114:117], v[188:191], v[204:207], v[114:117]
	v_mfma_f32_16x16x32_bf16 v[130:133], v[188:191], v[196:199], v[130:133]
	v_mfma_f32_16x16x32_bf16 v[138:141], v[184:187], v[200:203], v[138:141]
	v_mfma_f32_16x16x32_bf16 v[122:125], v[184:187], v[208:211], v[122:125]
	v_mfma_f32_16x16x32_bf16 v[106:109], v[184:187], v[216:219], v[106:109]
	v_mfma_f32_16x16x32_bf16 v[82:85], v[184:187], v[238:241], v[82:85]
	v_mfma_f32_16x16x32_bf16 v[66:69], v[192:195], v[238:241], v[66:69]
	v_mfma_f32_16x16x32_bf16 v[98:101], v[192:195], v[216:219], v[98:101]
	v_mfma_f32_16x16x32_bf16 v[114:117], v[192:195], v[208:211], v[114:117]
	v_mfma_f32_16x16x32_bf16 v[130:133], v[192:195], v[200:203], v[130:133]
	s_setprio 0
	s_barrier
	s_add_i32 s0, s0, s37
	v_lshl_add_u64 v[168:169], v[168:169], 0, s[76:77]
	s_mov_b32 m0, s0
	ds_read_b128 v[196:199], v177 offset:49152
	ds_read_b128 v[200:203], v177 offset:50176
	ds_read_b128 v[204:207], v177 offset:51200
	ds_read_b128 v[208:211], v177 offset:52224
	ds_read_b128 v[212:215], v177 offset:53248
	ds_read_b128 v[216:219], v177 offset:54272
	ds_read_b128 v[230:233], v177 offset:55296
	ds_read_b128 v[238:241], v177 offset:56320
	global_load_lds_dwordx4 v[168:169], off
	s_add_i32 m0, s0, 0x2000
	s_add_u32 s56, s56, 0x40080
	v_lshl_add_u64 v[168:169], v[242:243], 0, s[76:77]
	s_addc_u32 s57, s57, 0
	s_add_i32 s0, s83, s37
	global_load_lds_dwordx4 v[168:169], off
	v_lshl_add_u64 v[168:169], s[56:57], 0, v[150:151]
	s_mov_b32 m0, s0
	s_nop 0
	global_load_lds_dwordx4 v[168:169], off
	v_lshl_add_u64 v[168:169], s[56:57], 0, v[146:147]
	s_add_i32 m0, s0, 0x2000
	s_nop 0
	global_load_lds_dwordx4 v[168:169], off
	v_lshl_add_u64 v[168:169], v[244:245], 0, s[76:77]
	s_mov_b32 m0, s67
	s_nop 0
	global_load_lds_dwordx4 v[168:169], off
	v_lshl_add_u64 v[168:169], v[246:247], 0, s[76:77]
	s_mov_b32 m0, s68
	s_nop 0
	global_load_lds_dwordx4 v[168:169], off
	s_waitcnt vmcnt(8)
	s_waitcnt lgkmcnt(0)
	s_barrier
	s_setprio 1
	s_waitcnt lgkmcnt(0)
	v_mfma_f32_16x16x32_bf16 v[62:65], v[74:77], v[196:199], v[62:65]
	v_mfma_f32_16x16x32_bf16 v[46:49], v[74:77], v[204:207], v[46:49]
	v_mfma_f32_16x16x32_bf16 v[30:33], v[74:77], v[212:215], v[30:33]
	v_mfma_f32_16x16x32_bf16 v[14:17], v[74:77], v[230:233], v[14:17]
	v_mfma_f32_16x16x32_bf16 v[6:9], v[90:93], v[230:233], v[6:9]
	v_mfma_f32_16x16x32_bf16 v[22:25], v[90:93], v[212:215], v[22:25]
	v_mfma_f32_16x16x32_bf16 v[38:41], v[90:93], v[204:207], v[38:41]
	v_mfma_f32_16x16x32_bf16 v[54:57], v[90:93], v[196:199], v[54:57]
	v_mfma_f32_16x16x32_bf16 v[62:65], v[78:81], v[200:203], v[62:65]
	v_mfma_f32_16x16x32_bf16 v[46:49], v[78:81], v[208:211], v[46:49]
	v_mfma_f32_16x16x32_bf16 v[30:33], v[78:81], v[216:219], v[30:33]
	v_mfma_f32_16x16x32_bf16 v[14:17], v[78:81], v[238:241], v[14:17]
	v_mfma_f32_16x16x32_bf16 v[6:9], v[94:97], v[238:241], v[6:9]
	v_mfma_f32_16x16x32_bf16 v[22:25], v[94:97], v[216:219], v[22:25]
	v_mfma_f32_16x16x32_bf16 v[38:41], v[94:97], v[208:211], v[38:41]
	v_mfma_f32_16x16x32_bf16 v[54:57], v[94:97], v[200:203], v[54:57]
	s_setprio 0
	s_setprio 1
	v_mfma_f32_16x16x32_bf16 v[58:61], v[180:183], v[196:199], v[58:61]
	v_mfma_f32_16x16x32_bf16 v[42:45], v[180:183], v[204:207], v[42:45]
	v_mfma_f32_16x16x32_bf16 v[26:29], v[180:183], v[212:215], v[26:29]
	v_mfma_f32_16x16x32_bf16 v[10:13], v[180:183], v[230:233], v[10:13]
	v_mfma_f32_16x16x32_bf16 v[2:5], v[188:191], v[230:233], v[2:5]
	v_mfma_f32_16x16x32_bf16 v[18:21], v[188:191], v[212:215], v[18:21]
	v_mfma_f32_16x16x32_bf16 v[34:37], v[188:191], v[204:207], v[34:37]
	v_mfma_f32_16x16x32_bf16 v[50:53], v[188:191], v[196:199], v[50:53]
	v_mfma_f32_16x16x32_bf16 v[58:61], v[184:187], v[200:203], v[58:61]
	v_mfma_f32_16x16x32_bf16 v[42:45], v[184:187], v[208:211], v[42:45]
	v_mfma_f32_16x16x32_bf16 v[26:29], v[184:187], v[216:219], v[26:29]
	v_mfma_f32_16x16x32_bf16 v[10:13], v[184:187], v[238:241], v[10:13]
	v_mfma_f32_16x16x32_bf16 v[2:5], v[192:195], v[238:241], v[2:5]
	v_mfma_f32_16x16x32_bf16 v[18:21], v[192:195], v[216:219], v[18:21]
	v_mfma_f32_16x16x32_bf16 v[34:37], v[192:195], v[208:211], v[34:37]
	v_mfma_f32_16x16x32_bf16 v[50:53], v[192:195], v[200:203], v[50:53]
	s_setprio 0
	s_barrier
	s_add_i32 s82, s82, 2
	s_add_u32 s52, s52, 0x100
	s_addc_u32 s53, s53, 0
	s_add_u32 s73, s73, 0x100
	s_addc_u32 s75, s75, 0
	s_cmp_gt_u32 s82, 13
	s_cbranch_scc0 .LBB0_256
	s_and_b64 vcc, exec, s[10:11]
	s_cbranch_vccz .LBB0_259
	s_barrier

.LBB0_282:
	s_ashr_i32 s59, s58, 31
	s_lshl_b64 s[20:21], s[58:59], 19
	s_add_u32 s64, s26, s20
	s_addc_u32 s65, s27, s21
	s_and_b64 s[20:21], s[8:9], exec
	s_cselect_b32 s20, s65, s5
	s_cselect_b32 s21, s64, s4
	s_ashr_i32 s57, s56, 31
	s_lshl_b64 s[36:37], s[56:57], 19
	s_add_u32 s66, s35, s36
	s_addc_u32 s67, s40, s37
	s_and_b64 s[36:37], s[8:9], exec
	s_cselect_b32 s36, s67, s7
	s_cselect_b32 s37, s66, s6
	s_add_u32 s4, s4, 0x40080
	s_addc_u32 s5, s5, 0
	s_add_u32 s46, s6, 0x100
	s_addc_u32 s57, s7, 0
	s_mov_b32 s59, -2
	s_add_u32 s6, s4, 0xfffc0080
	s_addc_u32 s7, s5, -1
	s_add_i32 s82, 0, 0x10000
	s_cmp_eq_u32 s59, 12
	s_cselect_b32 s69, s20, s7
	s_cselect_b32 s68, s21, s6
	s_cselect_b32 s7, s36, s57
	s_cselect_b32 s6, s37, s46
	s_add_i32 s84, 0, 0x14000
	v_add_u32_e32 v142, s82, v202
	v_add_u32_e32 v158, s84, v202
	ds_read_b128 v[130:133], v142
	ds_read_b128 v[134:137], v142 offset:1024
	ds_read_b128 v[138:141], v142 offset:2048
	ds_read_b128 v[142:145], v142 offset:3072
	ds_read_b128 v[146:149], v158
	ds_read_b128 v[150:153], v158 offset:1024
	ds_read_b128 v[154:157], v158 offset:2048
	ds_read_b128 v[158:161], v158 offset:3072
	v_lshl_add_u64 v[218:219], s[4:5], 0, v[182:183]
	s_add_i32 m0, s87, 0xc000
	ds_read_b128 v[186:189], v204
	ds_read_b128 v[190:193], v204 offset:1024
	ds_read_b128 v[194:197], v204 offset:2048
	ds_read_b128 v[198:201], v204 offset:3072
	ds_read_b128 v[206:209], v204 offset:4096
	ds_read_b128 v[210:213], v204 offset:5120
	ds_read_b128 v[214:217], v204 offset:6144
	ds_read_b128 v[238:241], v204 offset:7168
	global_load_lds_dwordx4 v[218:219], off
	v_lshl_add_u64 v[218:219], s[4:5], 0, v[184:185]
	s_add_i32 m0, s87, 0xe000
	s_nop 0
	global_load_lds_dwordx4 v[218:219], off
	s_waitcnt vmcnt(8)
	s_waitcnt lgkmcnt(0)
	s_barrier
	s_setprio 1
	s_waitcnt lgkmcnt(0)
	v_mfma_f32_16x16x32_bf16 v[2:5], v[130:133], v[186:189], 0
	v_mfma_f32_16x16x32_bf16 v[30:33], v[130:133], v[194:197], 0
	v_mfma_f32_16x16x32_bf16 v[34:37], v[130:133], v[206:209], 0
	v_mfma_f32_16x16x32_bf16 v[62:65], v[130:133], v[214:217], 0
	v_mfma_f32_16x16x32_bf16 v[58:61], v[138:141], v[214:217], 0
	v_mfma_f32_16x16x32_bf16 v[42:45], v[138:141], v[206:209], 0
	v_mfma_f32_16x16x32_bf16 v[26:29], v[138:141], v[194:197], 0
	v_mfma_f32_16x16x32_bf16 v[6:9], v[138:141], v[186:189], 0
	v_mfma_f32_16x16x32_bf16 v[2:5], v[134:137], v[190:193], v[2:5]
	v_mfma_f32_16x16x32_bf16 v[30:33], v[134:137], v[198:201], v[30:33]
	v_mfma_f32_16x16x32_bf16 v[34:37], v[134:137], v[210:213], v[34:37]
	v_mfma_f32_16x16x32_bf16 v[62:65], v[134:137], v[238:241], v[62:65]
	v_mfma_f32_16x16x32_bf16 v[58:61], v[142:145], v[238:241], v[58:61]
	v_mfma_f32_16x16x32_bf16 v[42:45], v[142:145], v[210:213], v[42:45]
	v_mfma_f32_16x16x32_bf16 v[26:29], v[142:145], v[198:201], v[26:29]
	v_mfma_f32_16x16x32_bf16 v[6:9], v[142:145], v[190:193], v[6:9]
	s_setprio 0
	s_setprio 1
	v_mfma_f32_16x16x32_bf16 v[14:17], v[146:149], v[186:189], 0
	v_mfma_f32_16x16x32_bf16 v[22:25], v[146:149], v[194:197], 0
	v_mfma_f32_16x16x32_bf16 v[46:49], v[146:149], v[206:209], 0
	v_mfma_f32_16x16x32_bf16 v[54:57], v[146:149], v[214:217], 0
	v_mfma_f32_16x16x32_bf16 v[50:53], v[154:157], v[214:217], 0
	v_mfma_f32_16x16x32_bf16 v[38:41], v[154:157], v[206:209], 0
	v_mfma_f32_16x16x32_bf16 v[18:21], v[154:157], v[194:197], 0
	v_mfma_f32_16x16x32_bf16 v[10:13], v[154:157], v[186:189], 0
	v_mfma_f32_16x16x32_bf16 v[14:17], v[150:153], v[190:193], v[14:17]
	v_mfma_f32_16x16x32_bf16 v[22:25], v[150:153], v[198:201], v[22:25]
	v_mfma_f32_16x16x32_bf16 v[46:49], v[150:153], v[210:213], v[46:49]
	v_mfma_f32_16x16x32_bf16 v[54:57], v[150:153], v[238:241], v[54:57]
	v_mfma_f32_16x16x32_bf16 v[50:53], v[158:161], v[238:241], v[50:53]
	v_mfma_f32_16x16x32_bf16 v[38:41], v[158:161], v[210:213], v[38:41]
	v_mfma_f32_16x16x32_bf16 v[18:21], v[158:161], v[198:201], v[18:21]
	v_mfma_f32_16x16x32_bf16 v[10:13], v[158:161], v[190:193], v[10:13]
	s_setprio 0
	s_barrier
	s_add_i32 s82, s82, s41
	v_lshl_add_u64 v[218:219], s[6:7], 0, v[164:165]
	s_mov_b32 m0, s82
	ds_read_b128 v[186:189], v204 offset:16384
	ds_read_b128 v[190:193], v204 offset:17408
	ds_read_b128 v[194:197], v204 offset:18432
	ds_read_b128 v[198:201], v204 offset:19456
	ds_read_b128 v[206:209], v204 offset:20480
	ds_read_b128 v[210:213], v204 offset:21504
	ds_read_b128 v[214:217], v204 offset:22528
	ds_read_b128 v[238:241], v204 offset:23552
	global_load_lds_dwordx4 v[218:219], off
	s_add_i32 m0, s82, 0x2000
	s_add_u32 s82, s6, 0x40000
	v_lshl_add_u64 v[230:231], s[6:7], 0, v[162:163]
	s_addc_u32 s83, s7, 0
	s_add_i32 s84, s84, s41
	global_load_lds_dwordx4 v[230:231], off
	v_lshl_add_u64 v[232:233], s[82:83], 0, v[164:165]
	s_mov_b32 m0, s84
	v_lshl_add_u64 v[242:243], s[68:69], 0, v[162:163]
	global_load_lds_dwordx4 v[232:233], off
	v_lshl_add_u64 v[232:233], s[82:83], 0, v[162:163]
	s_add_i32 m0, s84, 0x2000
	s_nop 0
	global_load_lds_dwordx4 v[232:233], off
	v_lshl_add_u64 v[232:233], s[68:69], 0, v[164:165]
	s_mov_b32 m0, s87
	s_nop 0
	global_load_lds_dwordx4 v[232:233], off
	s_mov_b32 m0, s75
	s_nop 0
	global_load_lds_dwordx4 v[242:243], off
	s_waitcnt vmcnt(8)
	s_waitcnt lgkmcnt(0)
	s_barrier
	s_setprio 1
	s_waitcnt lgkmcnt(0)
	v_mfma_f32_16x16x32_bf16 v[74:77], v[130:133], v[186:189], 0
	v_mfma_f32_16x16x32_bf16 v[94:97], v[130:133], v[194:197], 0
	v_mfma_f32_16x16x32_bf16 v[106:109], v[130:133], v[206:209], 0
	v_mfma_f32_16x16x32_bf16 v[118:121], v[130:133], v[214:217], 0
	v_mfma_f32_16x16x32_bf16 v[114:117], v[138:141], v[214:217], 0
	v_mfma_f32_16x16x32_bf16 v[102:105], v[138:141], v[206:209], 0
	v_mfma_f32_16x16x32_bf16 v[90:93], v[138:141], v[194:197], 0
	v_mfma_f32_16x16x32_bf16 v[70:73], v[138:141], v[186:189], 0
	v_mfma_f32_16x16x32_bf16 v[74:77], v[134:137], v[190:193], v[74:77]
	v_mfma_f32_16x16x32_bf16 v[94:97], v[134:137], v[198:201], v[94:97]
	v_mfma_f32_16x16x32_bf16 v[106:109], v[134:137], v[210:213], v[106:109]
	v_mfma_f32_16x16x32_bf16 v[118:121], v[134:137], v[238:241], v[118:121]
	v_mfma_f32_16x16x32_bf16 v[114:117], v[142:145], v[238:241], v[114:117]
	v_mfma_f32_16x16x32_bf16 v[102:105], v[142:145], v[210:213], v[102:105]
	v_mfma_f32_16x16x32_bf16 v[90:93], v[142:145], v[198:201], v[90:93]
	v_mfma_f32_16x16x32_bf16 v[70:73], v[142:145], v[190:193], v[70:73]
	s_setprio 0
	s_setprio 1
	v_mfma_f32_16x16x32_bf16 v[78:81], v[146:149], v[186:189], 0
	v_mfma_f32_16x16x32_bf16 v[86:89], v[146:149], v[194:197], 0
	v_mfma_f32_16x16x32_bf16 v[110:113], v[146:149], v[206:209], 0
	v_mfma_f32_16x16x32_bf16 v[122:125], v[146:149], v[214:217], 0
	v_mfma_f32_16x16x32_bf16 v[126:129], v[154:157], v[214:217], 0
	v_mfma_f32_16x16x32_bf16 v[98:101], v[154:157], v[206:209], 0
	v_mfma_f32_16x16x32_bf16 v[82:85], v[154:157], v[194:197], 0
	v_mfma_f32_16x16x32_bf16 v[66:69], v[154:157], v[186:189], 0
	v_mfma_f32_16x16x32_bf16 v[78:81], v[150:153], v[190:193], v[78:81]
	v_mfma_f32_16x16x32_bf16 v[86:89], v[150:153], v[198:201], v[86:89]
	v_mfma_f32_16x16x32_bf16 v[110:113], v[150:153], v[210:213], v[110:113]
	v_mfma_f32_16x16x32_bf16 v[122:125], v[150:153], v[238:241], v[122:125]
	v_mfma_f32_16x16x32_bf16 v[126:129], v[158:161], v[238:241], v[126:129]
	v_mfma_f32_16x16x32_bf16 v[98:101], v[158:161], v[210:213], v[98:101]
	v_mfma_f32_16x16x32_bf16 v[82:85], v[158:161], v[198:201], v[82:85]
	v_mfma_f32_16x16x32_bf16 v[66:69], v[158:161], v[190:193], v[66:69]
	s_setprio 0
	s_barrier
	s_add_i32 s82, 0, 0x18000
	s_add_i32 s83, 0, 0x1c000
	v_add_u32_e32 v142, s82, v202
	v_add_u32_e32 v158, s83, v202
	ds_read_b128 v[130:133], v142
	ds_read_b128 v[134:137], v142 offset:1024
	ds_read_b128 v[138:141], v142 offset:2048
	ds_read_b128 v[142:145], v142 offset:3072
	ds_read_b128 v[146:149], v158
	ds_read_b128 v[150:153], v158 offset:1024
	ds_read_b128 v[154:157], v158 offset:2048
	ds_read_b128 v[158:161], v158 offset:3072
	s_add_u32 s68, s68, 0x40000
	s_addc_u32 s69, s69, 0
	s_mov_b32 m0, s72
	v_lshl_add_u64 v[244:245], s[68:69], 0, v[164:165]
	ds_read_b128 v[186:189], v204 offset:32768
	ds_read_b128 v[190:193], v204 offset:33792
	ds_read_b128 v[194:197], v204 offset:34816
	ds_read_b128 v[198:201], v204 offset:35840
	ds_read_b128 v[206:209], v204 offset:36864
	ds_read_b128 v[210:213], v204 offset:37888
	ds_read_b128 v[214:217], v204 offset:38912
	ds_read_b128 v[238:241], v204 offset:39936
	global_load_lds_dwordx4 v[244:245], off
	v_lshl_add_u64 v[244:245], s[68:69], 0, v[162:163]
	s_mov_b32 m0, s73
	s_nop 0
	global_load_lds_dwordx4 v[244:245], off
	s_waitcnt vmcnt(8)
	s_waitcnt lgkmcnt(0)
	s_barrier
	s_setprio 1
	s_waitcnt lgkmcnt(0)
	v_mfma_f32_16x16x32_bf16 v[2:5], v[130:133], v[186:189], v[2:5]
	v_mfma_f32_16x16x32_bf16 v[30:33], v[130:133], v[194:197], v[30:33]
	v_mfma_f32_16x16x32_bf16 v[34:37], v[130:133], v[206:209], v[34:37]
	v_mfma_f32_16x16x32_bf16 v[62:65], v[130:133], v[214:217], v[62:65]
	v_mfma_f32_16x16x32_bf16 v[58:61], v[138:141], v[214:217], v[58:61]
	v_mfma_f32_16x16x32_bf16 v[42:45], v[138:141], v[206:209], v[42:45]
	v_mfma_f32_16x16x32_bf16 v[26:29], v[138:141], v[194:197], v[26:29]
	v_mfma_f32_16x16x32_bf16 v[6:9], v[138:141], v[186:189], v[6:9]
	v_mfma_f32_16x16x32_bf16 v[2:5], v[134:137], v[190:193], v[2:5]
	v_mfma_f32_16x16x32_bf16 v[30:33], v[134:137], v[198:201], v[30:33]
	v_mfma_f32_16x16x32_bf16 v[34:37], v[134:137], v[210:213], v[34:37]
	v_mfma_f32_16x16x32_bf16 v[62:65], v[134:137], v[238:241], v[62:65]
	v_mfma_f32_16x16x32_bf16 v[58:61], v[142:145], v[238:241], v[58:61]
	v_mfma_f32_16x16x32_bf16 v[42:45], v[142:145], v[210:213], v[42:45]
	v_mfma_f32_16x16x32_bf16 v[26:29], v[142:145], v[198:201], v[26:29]
	v_mfma_f32_16x16x32_bf16 v[6:9], v[142:145], v[190:193], v[6:9]
	s_setprio 0
	s_setprio 1
	v_mfma_f32_16x16x32_bf16 v[14:17], v[146:149], v[186:189], v[14:17]
	v_mfma_f32_16x16x32_bf16 v[22:25], v[146:149], v[194:197], v[22:25]
	v_mfma_f32_16x16x32_bf16 v[46:49], v[146:149], v[206:209], v[46:49]
	v_mfma_f32_16x16x32_bf16 v[54:57], v[146:149], v[214:217], v[54:57]
	v_mfma_f32_16x16x32_bf16 v[50:53], v[154:157], v[214:217], v[50:53]
	v_mfma_f32_16x16x32_bf16 v[38:41], v[154:157], v[206:209], v[38:41]
	v_mfma_f32_16x16x32_bf16 v[18:21], v[154:157], v[194:197], v[18:21]
	v_mfma_f32_16x16x32_bf16 v[10:13], v[154:157], v[186:189], v[10:13]
	v_mfma_f32_16x16x32_bf16 v[14:17], v[150:153], v[190:193], v[14:17]
	v_mfma_f32_16x16x32_bf16 v[22:25], v[150:153], v[198:201], v[22:25]
	v_mfma_f32_16x16x32_bf16 v[46:49], v[150:153], v[210:213], v[46:49]
	v_mfma_f32_16x16x32_bf16 v[54:57], v[150:153], v[238:241], v[54:57]
	v_mfma_f32_16x16x32_bf16 v[50:53], v[158:161], v[238:241], v[50:53]
	v_mfma_f32_16x16x32_bf16 v[38:41], v[158:161], v[210:213], v[38:41]
	v_mfma_f32_16x16x32_bf16 v[18:21], v[158:161], v[198:201], v[18:21]
	v_mfma_f32_16x16x32_bf16 v[10:13], v[158:161], v[190:193], v[10:13]
	s_setprio 0
	s_barrier
	s_add_i32 s68, s82, s41
	v_lshl_add_u64 v[218:219], v[218:219], 0, s[76:77]
	s_mov_b32 m0, s68
	ds_read_b128 v[186:189], v204 offset:49152
	ds_read_b128 v[190:193], v204 offset:50176
	ds_read_b128 v[194:197], v204 offset:51200
	ds_read_b128 v[198:201], v204 offset:52224
	ds_read_b128 v[206:209], v204 offset:53248
	ds_read_b128 v[210:213], v204 offset:54272
	ds_read_b128 v[214:217], v204 offset:55296
	ds_read_b128 v[238:241], v204 offset:56320
	global_load_lds_dwordx4 v[218:219], off
	s_add_i32 m0, s68, 0x2000
	s_add_u32 s6, s6, 0x40080
	v_lshl_add_u64 v[218:219], v[230:231], 0, s[76:77]
	s_addc_u32 s7, s7, 0
	s_add_i32 s68, s83, s41
	global_load_lds_dwordx4 v[218:219], off
	v_lshl_add_u64 v[218:219], s[6:7], 0, v[164:165]
	s_mov_b32 m0, s68
	s_nop 0
	global_load_lds_dwordx4 v[218:219], off
	v_lshl_add_u64 v[218:219], s[6:7], 0, v[162:163]
	s_add_i32 m0, s68, 0x2000
	s_nop 0
	global_load_lds_dwordx4 v[218:219], off
	v_lshl_add_u64 v[218:219], v[232:233], 0, s[76:77]
	s_mov_b32 m0, s34
	s_nop 0
	global_load_lds_dwordx4 v[218:219], off
	v_lshl_add_u64 v[218:219], v[242:243], 0, s[76:77]
	s_mov_b32 m0, s30
	s_nop 0
	global_load_lds_dwordx4 v[218:219], off
	s_waitcnt vmcnt(8)
	s_waitcnt lgkmcnt(0)
	s_barrier
	s_setprio 1
	s_waitcnt lgkmcnt(0)
	v_mfma_f32_16x16x32_bf16 v[74:77], v[130:133], v[186:189], v[74:77]
	v_mfma_f32_16x16x32_bf16 v[94:97], v[130:133], v[194:197], v[94:97]
	v_mfma_f32_16x16x32_bf16 v[106:109], v[130:133], v[206:209], v[106:109]
	v_mfma_f32_16x16x32_bf16 v[118:121], v[130:133], v[214:217], v[118:121]
	v_mfma_f32_16x16x32_bf16 v[114:117], v[138:141], v[214:217], v[114:117]
	v_mfma_f32_16x16x32_bf16 v[102:105], v[138:141], v[206:209], v[102:105]
	v_mfma_f32_16x16x32_bf16 v[90:93], v[138:141], v[194:197], v[90:93]
	v_mfma_f32_16x16x32_bf16 v[70:73], v[138:141], v[186:189], v[70:73]
	v_mfma_f32_16x16x32_bf16 v[74:77], v[134:137], v[190:193], v[74:77]
	v_mfma_f32_16x16x32_bf16 v[94:97], v[134:137], v[198:201], v[94:97]
	v_mfma_f32_16x16x32_bf16 v[106:109], v[134:137], v[210:213], v[106:109]
	v_mfma_f32_16x16x32_bf16 v[118:121], v[134:137], v[238:241], v[118:121]
	v_mfma_f32_16x16x32_bf16 v[114:117], v[142:145], v[238:241], v[114:117]
	v_mfma_f32_16x16x32_bf16 v[102:105], v[142:145], v[210:213], v[102:105]
	v_mfma_f32_16x16x32_bf16 v[90:93], v[142:145], v[198:201], v[90:93]
	v_mfma_f32_16x16x32_bf16 v[70:73], v[142:145], v[190:193], v[70:73]
	s_setprio 0
	s_setprio 1
	v_mfma_f32_16x16x32_bf16 v[78:81], v[146:149], v[186:189], v[78:81]
	v_mfma_f32_16x16x32_bf16 v[86:89], v[146:149], v[194:197], v[86:89]
	v_mfma_f32_16x16x32_bf16 v[110:113], v[146:149], v[206:209], v[110:113]
	v_mfma_f32_16x16x32_bf16 v[122:125], v[146:149], v[214:217], v[122:125]
	v_mfma_f32_16x16x32_bf16 v[126:129], v[154:157], v[214:217], v[126:129]
	v_mfma_f32_16x16x32_bf16 v[98:101], v[154:157], v[206:209], v[98:101]
	v_mfma_f32_16x16x32_bf16 v[82:85], v[154:157], v[194:197], v[82:85]
	v_mfma_f32_16x16x32_bf16 v[66:69], v[154:157], v[186:189], v[66:69]
	v_mfma_f32_16x16x32_bf16 v[78:81], v[150:153], v[190:193], v[78:81]
	v_mfma_f32_16x16x32_bf16 v[86:89], v[150:153], v[198:201], v[86:89]
	v_mfma_f32_16x16x32_bf16 v[110:113], v[150:153], v[210:213], v[110:113]
	v_mfma_f32_16x16x32_bf16 v[122:125], v[150:153], v[238:241], v[122:125]
	v_mfma_f32_16x16x32_bf16 v[126:129], v[158:161], v[238:241], v[126:129]
	v_mfma_f32_16x16x32_bf16 v[98:101], v[158:161], v[210:213], v[98:101]
	v_mfma_f32_16x16x32_bf16 v[82:85], v[158:161], v[198:201], v[82:85]
	v_mfma_f32_16x16x32_bf16 v[66:69], v[158:161], v[190:193], v[66:69]
	s_setprio 0
	s_barrier
	s_add_i32 s59, s59, 2
	s_add_u32 s4, s4, 0x100
	s_addc_u32 s5, s5, 0
	s_add_u32 s46, s46, 0x100
	s_addc_u32 s57, s57, 0
.LBB0_283:
	s_add_u32 s6, s4, 0xfffc0080
	s_addc_u32 s7, s5, -1
	s_add_i32 s82, 0, 0x10000
	s_cmp_eq_u32 s59, 12
	s_cselect_b32 s69, s20, s7
	s_cselect_b32 s68, s21, s6
	s_cselect_b32 s7, s36, s57
	s_cselect_b32 s6, s37, s46
	s_add_i32 s84, 0, 0x14000
	v_add_u32_e32 v142, s82, v202
	v_add_u32_e32 v158, s84, v202
	ds_read_b128 v[130:133], v142
	ds_read_b128 v[134:137], v142 offset:1024
	ds_read_b128 v[138:141], v142 offset:2048
	ds_read_b128 v[142:145], v142 offset:3072
	ds_read_b128 v[146:149], v158
	ds_read_b128 v[150:153], v158 offset:1024
	ds_read_b128 v[154:157], v158 offset:2048
	ds_read_b128 v[158:161], v158 offset:3072
	v_lshl_add_u64 v[218:219], s[4:5], 0, v[182:183]
	s_add_i32 m0, s87, 0xc000
	ds_read_b128 v[186:189], v204
	ds_read_b128 v[190:193], v204 offset:1024
	ds_read_b128 v[194:197], v204 offset:2048
	ds_read_b128 v[198:201], v204 offset:3072
	ds_read_b128 v[206:209], v204 offset:4096
	ds_read_b128 v[210:213], v204 offset:5120
	ds_read_b128 v[214:217], v204 offset:6144
	ds_read_b128 v[238:241], v204 offset:7168
	global_load_lds_dwordx4 v[218:219], off
	v_lshl_add_u64 v[218:219], s[4:5], 0, v[184:185]
	s_add_i32 m0, s87, 0xe000
	s_nop 0
	global_load_lds_dwordx4 v[218:219], off
	s_waitcnt vmcnt(8)
	s_waitcnt lgkmcnt(0)
	s_barrier
	s_setprio 1
	s_waitcnt lgkmcnt(0)
	v_mfma_f32_16x16x32_bf16 v[2:5], v[130:133], v[186:189], v[2:5]
	v_mfma_f32_16x16x32_bf16 v[30:33], v[130:133], v[194:197], v[30:33]
	v_mfma_f32_16x16x32_bf16 v[34:37], v[130:133], v[206:209], v[34:37]
	v_mfma_f32_16x16x32_bf16 v[62:65], v[130:133], v[214:217], v[62:65]
	v_mfma_f32_16x16x32_bf16 v[58:61], v[138:141], v[214:217], v[58:61]
	v_mfma_f32_16x16x32_bf16 v[42:45], v[138:141], v[206:209], v[42:45]
	v_mfma_f32_16x16x32_bf16 v[26:29], v[138:141], v[194:197], v[26:29]
	v_mfma_f32_16x16x32_bf16 v[6:9], v[138:141], v[186:189], v[6:9]
	v_mfma_f32_16x16x32_bf16 v[2:5], v[134:137], v[190:193], v[2:5]
	v_mfma_f32_16x16x32_bf16 v[30:33], v[134:137], v[198:201], v[30:33]
	v_mfma_f32_16x16x32_bf16 v[34:37], v[134:137], v[210:213], v[34:37]
	v_mfma_f32_16x16x32_bf16 v[62:65], v[134:137], v[238:241], v[62:65]
	v_mfma_f32_16x16x32_bf16 v[58:61], v[142:145], v[238:241], v[58:61]
	v_mfma_f32_16x16x32_bf16 v[42:45], v[142:145], v[210:213], v[42:45]
	v_mfma_f32_16x16x32_bf16 v[26:29], v[142:145], v[198:201], v[26:29]
	v_mfma_f32_16x16x32_bf16 v[6:9], v[142:145], v[190:193], v[6:9]
	s_setprio 0
	s_setprio 1
	v_mfma_f32_16x16x32_bf16 v[14:17], v[146:149], v[186:189], v[14:17]
	v_mfma_f32_16x16x32_bf16 v[22:25], v[146:149], v[194:197], v[22:25]
	v_mfma_f32_16x16x32_bf16 v[46:49], v[146:149], v[206:209], v[46:49]
	v_mfma_f32_16x16x32_bf16 v[54:57], v[146:149], v[214:217], v[54:57]
	v_mfma_f32_16x16x32_bf16 v[50:53], v[154:157], v[214:217], v[50:53]
	v_mfma_f32_16x16x32_bf16 v[38:41], v[154:157], v[206:209], v[38:41]
	v_mfma_f32_16x16x32_bf16 v[18:21], v[154:157], v[194:197], v[18:21]
	v_mfma_f32_16x16x32_bf16 v[10:13], v[154:157], v[186:189], v[10:13]
	v_mfma_f32_16x16x32_bf16 v[14:17], v[150:153], v[190:193], v[14:17]
	v_mfma_f32_16x16x32_bf16 v[22:25], v[150:153], v[198:201], v[22:25]
	v_mfma_f32_16x16x32_bf16 v[46:49], v[150:153], v[210:213], v[46:49]
	v_mfma_f32_16x16x32_bf16 v[54:57], v[150:153], v[238:241], v[54:57]
	v_mfma_f32_16x16x32_bf16 v[50:53], v[158:161], v[238:241], v[50:53]
	v_mfma_f32_16x16x32_bf16 v[38:41], v[158:161], v[210:213], v[38:41]
	v_mfma_f32_16x16x32_bf16 v[18:21], v[158:161], v[198:201], v[18:21]
	v_mfma_f32_16x16x32_bf16 v[10:13], v[158:161], v[190:193], v[10:13]
	s_setprio 0
	s_barrier
	s_add_i32 s82, s82, s41
	v_lshl_add_u64 v[218:219], s[6:7], 0, v[164:165]
	s_mov_b32 m0, s82
	ds_read_b128 v[186:189], v204 offset:16384
	ds_read_b128 v[190:193], v204 offset:17408
	ds_read_b128 v[194:197], v204 offset:18432
	ds_read_b128 v[198:201], v204 offset:19456
	ds_read_b128 v[206:209], v204 offset:20480
	ds_read_b128 v[210:213], v204 offset:21504
	ds_read_b128 v[214:217], v204 offset:22528
	ds_read_b128 v[238:241], v204 offset:23552
	global_load_lds_dwordx4 v[218:219], off
	s_add_i32 m0, s82, 0x2000
	s_add_u32 s82, s6, 0x40000
	v_lshl_add_u64 v[230:231], s[6:7], 0, v[162:163]
	s_addc_u32 s83, s7, 0
	s_add_i32 s84, s84, s41
	global_load_lds_dwordx4 v[230:231], off
	v_lshl_add_u64 v[232:233], s[82:83], 0, v[164:165]
	s_mov_b32 m0, s84
	v_lshl_add_u64 v[242:243], s[68:69], 0, v[162:163]
	global_load_lds_dwordx4 v[232:233], off
	v_lshl_add_u64 v[232:233], s[82:83], 0, v[162:163]
	s_add_i32 m0, s84, 0x2000
	s_nop 0
	global_load_lds_dwordx4 v[232:233], off
	v_lshl_add_u64 v[232:233], s[68:69], 0, v[164:165]
	s_mov_b32 m0, s87
	s_nop 0
	global_load_lds_dwordx4 v[232:233], off
	s_mov_b32 m0, s75
	s_nop 0
	global_load_lds_dwordx4 v[242:243], off
	s_waitcnt vmcnt(8)
	s_waitcnt lgkmcnt(0)
	s_barrier
	s_setprio 1
	s_waitcnt lgkmcnt(0)
	v_mfma_f32_16x16x32_bf16 v[74:77], v[130:133], v[186:189], v[74:77]
	v_mfma_f32_16x16x32_bf16 v[94:97], v[130:133], v[194:197], v[94:97]
	v_mfma_f32_16x16x32_bf16 v[106:109], v[130:133], v[206:209], v[106:109]
	v_mfma_f32_16x16x32_bf16 v[118:121], v[130:133], v[214:217], v[118:121]
	v_mfma_f32_16x16x32_bf16 v[114:117], v[138:141], v[214:217], v[114:117]
	v_mfma_f32_16x16x32_bf16 v[102:105], v[138:141], v[206:209], v[102:105]
	v_mfma_f32_16x16x32_bf16 v[90:93], v[138:141], v[194:197], v[90:93]
	v_mfma_f32_16x16x32_bf16 v[70:73], v[138:141], v[186:189], v[70:73]
	v_mfma_f32_16x16x32_bf16 v[74:77], v[134:137], v[190:193], v[74:77]
	v_mfma_f32_16x16x32_bf16 v[94:97], v[134:137], v[198:201], v[94:97]
	v_mfma_f32_16x16x32_bf16 v[106:109], v[134:137], v[210:213], v[106:109]
	v_mfma_f32_16x16x32_bf16 v[118:121], v[134:137], v[238:241], v[118:121]
	v_mfma_f32_16x16x32_bf16 v[114:117], v[142:145], v[238:241], v[114:117]
	v_mfma_f32_16x16x32_bf16 v[102:105], v[142:145], v[210:213], v[102:105]
	v_mfma_f32_16x16x32_bf16 v[90:93], v[142:145], v[198:201], v[90:93]
	v_mfma_f32_16x16x32_bf16 v[70:73], v[142:145], v[190:193], v[70:73]
	s_setprio 0
	s_setprio 1
	v_mfma_f32_16x16x32_bf16 v[78:81], v[146:149], v[186:189], v[78:81]
	v_mfma_f32_16x16x32_bf16 v[86:89], v[146:149], v[194:197], v[86:89]
	v_mfma_f32_16x16x32_bf16 v[110:113], v[146:149], v[206:209], v[110:113]
	v_mfma_f32_16x16x32_bf16 v[122:125], v[146:149], v[214:217], v[122:125]
	v_mfma_f32_16x16x32_bf16 v[126:129], v[154:157], v[214:217], v[126:129]
	v_mfma_f32_16x16x32_bf16 v[98:101], v[154:157], v[206:209], v[98:101]
	v_mfma_f32_16x16x32_bf16 v[82:85], v[154:157], v[194:197], v[82:85]
	v_mfma_f32_16x16x32_bf16 v[66:69], v[154:157], v[186:189], v[66:69]
	v_mfma_f32_16x16x32_bf16 v[78:81], v[150:153], v[190:193], v[78:81]
	v_mfma_f32_16x16x32_bf16 v[86:89], v[150:153], v[198:201], v[86:89]
	v_mfma_f32_16x16x32_bf16 v[110:113], v[150:153], v[210:213], v[110:113]
	v_mfma_f32_16x16x32_bf16 v[122:125], v[150:153], v[238:241], v[122:125]
	v_mfma_f32_16x16x32_bf16 v[126:129], v[158:161], v[238:241], v[126:129]
	v_mfma_f32_16x16x32_bf16 v[98:101], v[158:161], v[210:213], v[98:101]
	v_mfma_f32_16x16x32_bf16 v[82:85], v[158:161], v[198:201], v[82:85]
	v_mfma_f32_16x16x32_bf16 v[66:69], v[158:161], v[190:193], v[66:69]
	s_setprio 0
	s_barrier
	s_add_i32 s82, 0, 0x18000
	s_add_i32 s83, 0, 0x1c000
	v_add_u32_e32 v142, s82, v202
	v_add_u32_e32 v158, s83, v202
	ds_read_b128 v[130:133], v142
	ds_read_b128 v[134:137], v142 offset:1024
	ds_read_b128 v[138:141], v142 offset:2048
	ds_read_b128 v[142:145], v142 offset:3072
	ds_read_b128 v[146:149], v158
	ds_read_b128 v[150:153], v158 offset:1024
	ds_read_b128 v[154:157], v158 offset:2048
	ds_read_b128 v[158:161], v158 offset:3072
	s_add_u32 s68, s68, 0x40000
	s_addc_u32 s69, s69, 0
	s_mov_b32 m0, s72
	v_lshl_add_u64 v[244:245], s[68:69], 0, v[164:165]
	ds_read_b128 v[186:189], v204 offset:32768
	ds_read_b128 v[190:193], v204 offset:33792
	ds_read_b128 v[194:197], v204 offset:34816
	ds_read_b128 v[198:201], v204 offset:35840
	ds_read_b128 v[206:209], v204 offset:36864
	ds_read_b128 v[210:213], v204 offset:37888
	ds_read_b128 v[214:217], v204 offset:38912
	ds_read_b128 v[238:241], v204 offset:39936
	global_load_lds_dwordx4 v[244:245], off
	v_lshl_add_u64 v[244:245], s[68:69], 0, v[162:163]
	s_mov_b32 m0, s73
	s_nop 0
	global_load_lds_dwordx4 v[244:245], off
	s_waitcnt vmcnt(8)
	s_waitcnt lgkmcnt(0)
	s_barrier
	s_setprio 1
	s_waitcnt lgkmcnt(0)
	v_mfma_f32_16x16x32_bf16 v[2:5], v[130:133], v[186:189], v[2:5]
	v_mfma_f32_16x16x32_bf16 v[30:33], v[130:133], v[194:197], v[30:33]
	v_mfma_f32_16x16x32_bf16 v[34:37], v[130:133], v[206:209], v[34:37]
	v_mfma_f32_16x16x32_bf16 v[62:65], v[130:133], v[214:217], v[62:65]
	v_mfma_f32_16x16x32_bf16 v[58:61], v[138:141], v[214:217], v[58:61]
	v_mfma_f32_16x16x32_bf16 v[42:45], v[138:141], v[206:209], v[42:45]
	v_mfma_f32_16x16x32_bf16 v[26:29], v[138:141], v[194:197], v[26:29]
	v_mfma_f32_16x16x32_bf16 v[6:9], v[138:141], v[186:189], v[6:9]
	v_mfma_f32_16x16x32_bf16 v[2:5], v[134:137], v[190:193], v[2:5]
	v_mfma_f32_16x16x32_bf16 v[30:33], v[134:137], v[198:201], v[30:33]
	v_mfma_f32_16x16x32_bf16 v[34:37], v[134:137], v[210:213], v[34:37]
	v_mfma_f32_16x16x32_bf16 v[62:65], v[134:137], v[238:241], v[62:65]
	v_mfma_f32_16x16x32_bf16 v[58:61], v[142:145], v[238:241], v[58:61]
	v_mfma_f32_16x16x32_bf16 v[42:45], v[142:145], v[210:213], v[42:45]
	v_mfma_f32_16x16x32_bf16 v[26:29], v[142:145], v[198:201], v[26:29]
	v_mfma_f32_16x16x32_bf16 v[6:9], v[142:145], v[190:193], v[6:9]
	s_setprio 0
	s_setprio 1
	v_mfma_f32_16x16x32_bf16 v[14:17], v[146:149], v[186:189], v[14:17]
	v_mfma_f32_16x16x32_bf16 v[22:25], v[146:149], v[194:197], v[22:25]
	v_mfma_f32_16x16x32_bf16 v[46:49], v[146:149], v[206:209], v[46:49]
	v_mfma_f32_16x16x32_bf16 v[54:57], v[146:149], v[214:217], v[54:57]
	v_mfma_f32_16x16x32_bf16 v[50:53], v[154:157], v[214:217], v[50:53]
	v_mfma_f32_16x16x32_bf16 v[38:41], v[154:157], v[206:209], v[38:41]
	v_mfma_f32_16x16x32_bf16 v[18:21], v[154:157], v[194:197], v[18:21]
	v_mfma_f32_16x16x32_bf16 v[10:13], v[154:157], v[186:189], v[10:13]
	v_mfma_f32_16x16x32_bf16 v[14:17], v[150:153], v[190:193], v[14:17]
	v_mfma_f32_16x16x32_bf16 v[22:25], v[150:153], v[198:201], v[22:25]
	v_mfma_f32_16x16x32_bf16 v[46:49], v[150:153], v[210:213], v[46:49]
	v_mfma_f32_16x16x32_bf16 v[54:57], v[150:153], v[238:241], v[54:57]
	v_mfma_f32_16x16x32_bf16 v[50:53], v[158:161], v[238:241], v[50:53]
	v_mfma_f32_16x16x32_bf16 v[38:41], v[158:161], v[210:213], v[38:41]
	v_mfma_f32_16x16x32_bf16 v[18:21], v[158:161], v[198:201], v[18:21]
	v_mfma_f32_16x16x32_bf16 v[10:13], v[158:161], v[190:193], v[10:13]
	s_setprio 0
	s_barrier
	s_add_i32 s68, s82, s41
	v_lshl_add_u64 v[218:219], v[218:219], 0, s[76:77]
	s_mov_b32 m0, s68
	ds_read_b128 v[186:189], v204 offset:49152
	ds_read_b128 v[190:193], v204 offset:50176
	ds_read_b128 v[194:197], v204 offset:51200
	ds_read_b128 v[198:201], v204 offset:52224
	ds_read_b128 v[206:209], v204 offset:53248
	ds_read_b128 v[210:213], v204 offset:54272
	ds_read_b128 v[214:217], v204 offset:55296
	ds_read_b128 v[238:241], v204 offset:56320
	global_load_lds_dwordx4 v[218:219], off
	s_add_i32 m0, s68, 0x2000
	s_add_u32 s6, s6, 0x40080
	v_lshl_add_u64 v[218:219], v[230:231], 0, s[76:77]
	s_addc_u32 s7, s7, 0
	s_add_i32 s68, s83, s41
	global_load_lds_dwordx4 v[218:219], off
	v_lshl_add_u64 v[218:219], s[6:7], 0, v[164:165]
	s_mov_b32 m0, s68
	s_nop 0
	global_load_lds_dwordx4 v[218:219], off
	v_lshl_add_u64 v[218:219], s[6:7], 0, v[162:163]
	s_add_i32 m0, s68, 0x2000
	s_nop 0
	global_load_lds_dwordx4 v[218:219], off
	v_lshl_add_u64 v[218:219], v[232:233], 0, s[76:77]
	s_mov_b32 m0, s34
	s_nop 0
	global_load_lds_dwordx4 v[218:219], off
	v_lshl_add_u64 v[218:219], v[242:243], 0, s[76:77]
	s_mov_b32 m0, s30
	s_nop 0
	global_load_lds_dwordx4 v[218:219], off
	s_waitcnt vmcnt(8)
	s_waitcnt lgkmcnt(0)
	s_barrier
	s_setprio 1
	s_waitcnt lgkmcnt(0)
	v_mfma_f32_16x16x32_bf16 v[74:77], v[130:133], v[186:189], v[74:77]
	v_mfma_f32_16x16x32_bf16 v[94:97], v[130:133], v[194:197], v[94:97]
	v_mfma_f32_16x16x32_bf16 v[106:109], v[130:133], v[206:209], v[106:109]
	v_mfma_f32_16x16x32_bf16 v[118:121], v[130:133], v[214:217], v[118:121]
	v_mfma_f32_16x16x32_bf16 v[114:117], v[138:141], v[214:217], v[114:117]
	v_mfma_f32_16x16x32_bf16 v[102:105], v[138:141], v[206:209], v[102:105]
	v_mfma_f32_16x16x32_bf16 v[90:93], v[138:141], v[194:197], v[90:93]
	v_mfma_f32_16x16x32_bf16 v[70:73], v[138:141], v[186:189], v[70:73]
	v_mfma_f32_16x16x32_bf16 v[74:77], v[134:137], v[190:193], v[74:77]
	v_mfma_f32_16x16x32_bf16 v[94:97], v[134:137], v[198:201], v[94:97]
	v_mfma_f32_16x16x32_bf16 v[106:109], v[134:137], v[210:213], v[106:109]
	v_mfma_f32_16x16x32_bf16 v[118:121], v[134:137], v[238:241], v[118:121]
	v_mfma_f32_16x16x32_bf16 v[114:117], v[142:145], v[238:241], v[114:117]
	v_mfma_f32_16x16x32_bf16 v[102:105], v[142:145], v[210:213], v[102:105]
	v_mfma_f32_16x16x32_bf16 v[90:93], v[142:145], v[198:201], v[90:93]
	v_mfma_f32_16x16x32_bf16 v[70:73], v[142:145], v[190:193], v[70:73]
	s_setprio 0
	s_setprio 1
	v_mfma_f32_16x16x32_bf16 v[78:81], v[146:149], v[186:189], v[78:81]
	v_mfma_f32_16x16x32_bf16 v[86:89], v[146:149], v[194:197], v[86:89]
	v_mfma_f32_16x16x32_bf16 v[110:113], v[146:149], v[206:209], v[110:113]
	v_mfma_f32_16x16x32_bf16 v[122:125], v[146:149], v[214:217], v[122:125]
	v_mfma_f32_16x16x32_bf16 v[126:129], v[154:157], v[214:217], v[126:129]
	v_mfma_f32_16x16x32_bf16 v[98:101], v[154:157], v[206:209], v[98:101]
	v_mfma_f32_16x16x32_bf16 v[82:85], v[154:157], v[194:197], v[82:85]
	v_mfma_f32_16x16x32_bf16 v[66:69], v[154:157], v[186:189], v[66:69]
	v_mfma_f32_16x16x32_bf16 v[78:81], v[150:153], v[190:193], v[78:81]
	v_mfma_f32_16x16x32_bf16 v[86:89], v[150:153], v[198:201], v[86:89]
	v_mfma_f32_16x16x32_bf16 v[110:113], v[150:153], v[210:213], v[110:113]
	v_mfma_f32_16x16x32_bf16 v[122:125], v[150:153], v[238:241], v[122:125]
	v_mfma_f32_16x16x32_bf16 v[126:129], v[158:161], v[238:241], v[126:129]
	v_mfma_f32_16x16x32_bf16 v[98:101], v[158:161], v[210:213], v[98:101]
	v_mfma_f32_16x16x32_bf16 v[82:85], v[158:161], v[198:201], v[82:85]
	v_mfma_f32_16x16x32_bf16 v[66:69], v[158:161], v[190:193], v[66:69]
	s_setprio 0
	s_barrier
	s_add_i32 s59, s59, 2
	s_add_u32 s4, s4, 0x100
	s_addc_u32 s5, s5, 0
	s_add_u32 s46, s46, 0x100
	s_addc_u32 s57, s57, 0
	s_cmp_gt_u32 s59, 13
	s_cbranch_scc0 .LBB0_283
	s_and_b64 vcc, exec, s[42:43]
	s_cbranch_vccz .LBB0_286
	s_barrier

.LBB0_670:
	s_add_u32 s6, s58, 0x80
	s_addc_u32 s7, s59, 0
	s_add_u32 s21, s56, 0x100
	s_addc_u32 s26, s57, 0
	s_mov_b32 s27, 0
	s_add_i32 s46, s27, 2
	s_add_u32 s0, s6, 0x80
	s_addc_u32 s56, s7, 0
	s_add_i32 vcc_lo, 0, 0x10000
	s_cmp_eq_u32 s72, s27
	s_cselect_b32 s57, s51, s56
	s_cselect_b32 s56, s50, s0
	s_cselect_b32 s59, s53, s26
	s_cselect_b32 s58, s52, s21
	s_add_i32 s0, 0, 0x14000
	v_add_u32_e32 v70, vcc_lo, v237
	v_add_u32_e32 v94, s0, v237
	ds_read_b128 v[58:61], v70
	ds_read_b128 v[62:65], v70 offset:1024
	ds_read_b128 v[66:69], v70 offset:2048
	ds_read_b128 v[70:73], v70 offset:3072
	ds_read_b128 v[82:85], v94
	ds_read_b128 v[86:89], v94 offset:1024
	ds_read_b128 v[90:93], v94 offset:2048
	ds_read_b128 v[94:97], v94 offset:3072
	v_lshl_add_u64 v[210:211], s[6:7], 0, v[194:195]
	s_add_i32 m0, s64, 0xc000
	ds_read_b128 v[162:165], v239
	ds_read_b128 v[166:169], v239 offset:1024
	ds_read_b128 v[170:173], v239 offset:2048
	ds_read_b128 v[174:177], v239 offset:3072
	ds_read_b128 v[178:181], v239 offset:4096
	ds_read_b128 v[198:201], v239 offset:5120
	ds_read_b128 v[202:205], v239 offset:6144
	ds_read_b128 v[206:209], v239 offset:7168
	global_load_lds_dwordx4 v[210:211], off
	v_lshl_add_u64 v[210:211], s[6:7], 0, v[196:197]
	s_add_i32 m0, s64, 0xe000
	s_nop 0
	global_load_lds_dwordx4 v[210:211], off
	s_waitcnt vmcnt(8)
	s_waitcnt lgkmcnt(0)
	s_barrier
	s_setprio 1
	s_waitcnt lgkmcnt(0)
	v_mfma_f32_16x16x32_bf16 v[158:161], v[58:61], v[162:165], 0
	v_mfma_f32_16x16x32_bf16 v[142:145], v[58:61], v[170:173], 0
	v_mfma_f32_16x16x32_bf16 v[126:129], v[58:61], v[178:181], 0
	v_mfma_f32_16x16x32_bf16 v[110:113], v[58:61], v[202:205], 0
	v_mfma_f32_16x16x32_bf16 v[106:109], v[66:69], v[202:205], 0
	v_mfma_f32_16x16x32_bf16 v[122:125], v[66:69], v[178:181], 0
	v_mfma_f32_16x16x32_bf16 v[138:141], v[66:69], v[170:173], 0
	v_mfma_f32_16x16x32_bf16 v[154:157], v[66:69], v[162:165], 0
	v_mfma_f32_16x16x32_bf16 v[158:161], v[62:65], v[166:169], v[158:161]
	v_mfma_f32_16x16x32_bf16 v[142:145], v[62:65], v[174:177], v[142:145]
	v_mfma_f32_16x16x32_bf16 v[126:129], v[62:65], v[198:201], v[126:129]
	v_mfma_f32_16x16x32_bf16 v[110:113], v[62:65], v[206:209], v[110:113]
	v_mfma_f32_16x16x32_bf16 v[106:109], v[70:73], v[206:209], v[106:109]
	v_mfma_f32_16x16x32_bf16 v[122:125], v[70:73], v[198:201], v[122:125]
	v_mfma_f32_16x16x32_bf16 v[138:141], v[70:73], v[174:177], v[138:141]
	v_mfma_f32_16x16x32_bf16 v[154:157], v[70:73], v[166:169], v[154:157]
	s_setprio 0
	s_setprio 1
	v_mfma_f32_16x16x32_bf16 v[150:153], v[82:85], v[162:165], 0
	v_mfma_f32_16x16x32_bf16 v[134:137], v[82:85], v[170:173], 0
	v_mfma_f32_16x16x32_bf16 v[118:121], v[82:85], v[178:181], 0
	v_mfma_f32_16x16x32_bf16 v[102:105], v[82:85], v[202:205], 0
	v_mfma_f32_16x16x32_bf16 v[98:101], v[90:93], v[202:205], 0
	v_mfma_f32_16x16x32_bf16 v[114:117], v[90:93], v[178:181], 0
	v_mfma_f32_16x16x32_bf16 v[130:133], v[90:93], v[170:173], 0
	v_mfma_f32_16x16x32_bf16 v[146:149], v[90:93], v[162:165], 0
	v_mfma_f32_16x16x32_bf16 v[150:153], v[86:89], v[166:169], v[150:153]
	v_mfma_f32_16x16x32_bf16 v[134:137], v[86:89], v[174:177], v[134:137]
	v_mfma_f32_16x16x32_bf16 v[118:121], v[86:89], v[198:201], v[118:121]
	v_mfma_f32_16x16x32_bf16 v[102:105], v[86:89], v[206:209], v[102:105]
	v_mfma_f32_16x16x32_bf16 v[98:101], v[94:97], v[206:209], v[98:101]
	v_mfma_f32_16x16x32_bf16 v[114:117], v[94:97], v[198:201], v[114:117]
	v_mfma_f32_16x16x32_bf16 v[130:133], v[94:97], v[174:177], v[130:133]
	v_mfma_f32_16x16x32_bf16 v[146:149], v[94:97], v[166:169], v[146:149]
	s_setprio 0
	s_barrier
	s_add_i32 s27, vcc_lo, s61
	v_lshl_add_u64 v[210:211], s[58:59], 0, v[186:187]
	s_mov_b32 m0, s27
	ds_read_b128 v[162:165], v239 offset:16384
	ds_read_b128 v[166:169], v239 offset:17408
	ds_read_b128 v[170:173], v239 offset:18432
	ds_read_b128 v[174:177], v239 offset:19456
	ds_read_b128 v[178:181], v239 offset:20480
	ds_read_b128 v[198:201], v239 offset:21504
	ds_read_b128 v[202:205], v239 offset:22528
	ds_read_b128 v[206:209], v239 offset:23552
	global_load_lds_dwordx4 v[210:211], off
	s_add_i32 m0, s27, 0x2000
	v_lshl_add_u64 v[212:213], s[58:59], 0, v[182:183]
	s_add_u32 s58, s58, s12
	s_addc_u32 s59, s59, 0
	s_add_i32 s0, s0, s61
	global_load_lds_dwordx4 v[212:213], off
	v_lshl_add_u64 v[214:215], s[58:59], 0, v[186:187]
	s_mov_b32 m0, s0
	v_lshl_add_u64 v[216:217], s[58:59], 0, v[182:183]
	global_load_lds_dwordx4 v[214:215], off
	s_add_i32 m0, s0, 0x2000
	v_lshl_add_u64 v[218:219], s[56:57], 0, v[188:189]
	global_load_lds_dwordx4 v[216:217], off
	s_mov_b32 m0, s64
	v_lshl_add_u64 v[230:231], s[56:57], 0, v[184:185]
	global_load_lds_dwordx4 v[218:219], off
	s_mov_b32 m0, s65
	s_nop 0
	global_load_lds_dwordx4 v[230:231], off
	s_waitcnt vmcnt(8)
	s_waitcnt lgkmcnt(0)
	s_barrier
	s_setprio 1
	s_waitcnt lgkmcnt(0)
	v_mfma_f32_16x16x32_bf16 v[78:81], v[58:61], v[162:165], 0
	v_mfma_f32_16x16x32_bf16 v[46:49], v[58:61], v[170:173], 0
	v_mfma_f32_16x16x32_bf16 v[30:33], v[58:61], v[178:181], 0
	v_mfma_f32_16x16x32_bf16 v[14:17], v[58:61], v[202:205], 0
	v_mfma_f32_16x16x32_bf16 v[10:13], v[66:69], v[202:205], 0
	v_mfma_f32_16x16x32_bf16 v[26:29], v[66:69], v[178:181], 0
	v_mfma_f32_16x16x32_bf16 v[42:45], v[66:69], v[170:173], 0
	v_mfma_f32_16x16x32_bf16 v[74:77], v[66:69], v[162:165], 0
	v_mfma_f32_16x16x32_bf16 v[78:81], v[62:65], v[166:169], v[78:81]
	v_mfma_f32_16x16x32_bf16 v[46:49], v[62:65], v[174:177], v[46:49]
	v_mfma_f32_16x16x32_bf16 v[30:33], v[62:65], v[198:201], v[30:33]
	v_mfma_f32_16x16x32_bf16 v[14:17], v[62:65], v[206:209], v[14:17]
	v_mfma_f32_16x16x32_bf16 v[10:13], v[70:73], v[206:209], v[10:13]
	v_mfma_f32_16x16x32_bf16 v[26:29], v[70:73], v[198:201], v[26:29]
	v_mfma_f32_16x16x32_bf16 v[42:45], v[70:73], v[174:177], v[42:45]
	v_mfma_f32_16x16x32_bf16 v[74:77], v[70:73], v[166:169], v[74:77]
	s_setprio 0
	s_setprio 1
	v_mfma_f32_16x16x32_bf16 v[54:57], v[82:85], v[162:165], 0
	v_mfma_f32_16x16x32_bf16 v[38:41], v[82:85], v[170:173], 0
	v_mfma_f32_16x16x32_bf16 v[22:25], v[82:85], v[178:181], 0
	v_mfma_f32_16x16x32_bf16 v[6:9], v[82:85], v[202:205], 0
	v_mfma_f32_16x16x32_bf16 v[2:5], v[90:93], v[202:205], 0
	v_mfma_f32_16x16x32_bf16 v[18:21], v[90:93], v[178:181], 0
	v_mfma_f32_16x16x32_bf16 v[34:37], v[90:93], v[170:173], 0
	v_mfma_f32_16x16x32_bf16 v[50:53], v[90:93], v[162:165], 0
	v_mfma_f32_16x16x32_bf16 v[54:57], v[86:89], v[166:169], v[54:57]
	v_mfma_f32_16x16x32_bf16 v[38:41], v[86:89], v[174:177], v[38:41]
	v_mfma_f32_16x16x32_bf16 v[22:25], v[86:89], v[198:201], v[22:25]
	v_mfma_f32_16x16x32_bf16 v[6:9], v[86:89], v[206:209], v[6:9]
	v_mfma_f32_16x16x32_bf16 v[2:5], v[94:97], v[206:209], v[2:5]
	v_mfma_f32_16x16x32_bf16 v[18:21], v[94:97], v[198:201], v[18:21]
	v_mfma_f32_16x16x32_bf16 v[34:37], v[94:97], v[174:177], v[34:37]
	v_mfma_f32_16x16x32_bf16 v[50:53], v[94:97], v[166:169], v[50:53]
	s_setprio 0
	s_barrier
	s_add_i32 s0, 0, 0x18000
	s_add_i32 s27, 0, 0x1c000
	v_add_u32_e32 v70, s0, v237
	v_add_u32_e32 v94, s27, v237
	ds_read_b128 v[58:61], v70
	ds_read_b128 v[62:65], v70 offset:1024
	ds_read_b128 v[66:69], v70 offset:2048
	ds_read_b128 v[70:73], v70 offset:3072
	ds_read_b128 v[82:85], v94
	ds_read_b128 v[86:89], v94 offset:1024
	ds_read_b128 v[90:93], v94 offset:2048
	ds_read_b128 v[94:97], v94 offset:3072
	s_add_u32 s56, s56, s12
	s_addc_u32 s57, s57, 0
	s_mov_b32 m0, s66
	v_lshl_add_u64 v[232:233], s[56:57], 0, v[188:189]
	ds_read_b128 v[162:165], v239 offset:32768
	ds_read_b128 v[166:169], v239 offset:33792
	ds_read_b128 v[170:173], v239 offset:34816
	ds_read_b128 v[174:177], v239 offset:35840
	ds_read_b128 v[178:181], v239 offset:36864
	ds_read_b128 v[198:201], v239 offset:37888
	ds_read_b128 v[202:205], v239 offset:38912
	ds_read_b128 v[206:209], v239 offset:39936
	global_load_lds_dwordx4 v[232:233], off
	v_lshl_add_u64 v[232:233], s[56:57], 0, v[184:185]
	s_mov_b32 m0, s67
	s_nop 0
	global_load_lds_dwordx4 v[232:233], off
	s_waitcnt vmcnt(8)
	s_waitcnt lgkmcnt(0)
	s_barrier
	s_setprio 1
	s_waitcnt lgkmcnt(0)
	v_mfma_f32_16x16x32_bf16 v[158:161], v[58:61], v[162:165], v[158:161]
	v_mfma_f32_16x16x32_bf16 v[142:145], v[58:61], v[170:173], v[142:145]
	v_mfma_f32_16x16x32_bf16 v[126:129], v[58:61], v[178:181], v[126:129]
	v_mfma_f32_16x16x32_bf16 v[110:113], v[58:61], v[202:205], v[110:113]
	v_mfma_f32_16x16x32_bf16 v[106:109], v[66:69], v[202:205], v[106:109]
	v_mfma_f32_16x16x32_bf16 v[122:125], v[66:69], v[178:181], v[122:125]
	v_mfma_f32_16x16x32_bf16 v[138:141], v[66:69], v[170:173], v[138:141]
	v_mfma_f32_16x16x32_bf16 v[154:157], v[66:69], v[162:165], v[154:157]
	v_mfma_f32_16x16x32_bf16 v[158:161], v[62:65], v[166:169], v[158:161]
	v_mfma_f32_16x16x32_bf16 v[142:145], v[62:65], v[174:177], v[142:145]
	v_mfma_f32_16x16x32_bf16 v[126:129], v[62:65], v[198:201], v[126:129]
	v_mfma_f32_16x16x32_bf16 v[110:113], v[62:65], v[206:209], v[110:113]
	v_mfma_f32_16x16x32_bf16 v[106:109], v[70:73], v[206:209], v[106:109]
	v_mfma_f32_16x16x32_bf16 v[122:125], v[70:73], v[198:201], v[122:125]
	v_mfma_f32_16x16x32_bf16 v[138:141], v[70:73], v[174:177], v[138:141]
	v_mfma_f32_16x16x32_bf16 v[154:157], v[70:73], v[166:169], v[154:157]
	s_setprio 0
	s_setprio 1
	v_mfma_f32_16x16x32_bf16 v[150:153], v[82:85], v[162:165], v[150:153]
	v_mfma_f32_16x16x32_bf16 v[134:137], v[82:85], v[170:173], v[134:137]
	v_mfma_f32_16x16x32_bf16 v[118:121], v[82:85], v[178:181], v[118:121]
	v_mfma_f32_16x16x32_bf16 v[102:105], v[82:85], v[202:205], v[102:105]
	v_mfma_f32_16x16x32_bf16 v[98:101], v[90:93], v[202:205], v[98:101]
	v_mfma_f32_16x16x32_bf16 v[114:117], v[90:93], v[178:181], v[114:117]
	v_mfma_f32_16x16x32_bf16 v[130:133], v[90:93], v[170:173], v[130:133]
	v_mfma_f32_16x16x32_bf16 v[146:149], v[90:93], v[162:165], v[146:149]
	v_mfma_f32_16x16x32_bf16 v[150:153], v[86:89], v[166:169], v[150:153]
	v_mfma_f32_16x16x32_bf16 v[134:137], v[86:89], v[174:177], v[134:137]
	v_mfma_f32_16x16x32_bf16 v[118:121], v[86:89], v[198:201], v[118:121]
	v_mfma_f32_16x16x32_bf16 v[102:105], v[86:89], v[206:209], v[102:105]
	v_mfma_f32_16x16x32_bf16 v[98:101], v[94:97], v[206:209], v[98:101]
	v_mfma_f32_16x16x32_bf16 v[114:117], v[94:97], v[198:201], v[114:117]
	v_mfma_f32_16x16x32_bf16 v[130:133], v[94:97], v[174:177], v[130:133]
	v_mfma_f32_16x16x32_bf16 v[146:149], v[94:97], v[166:169], v[146:149]
	s_setprio 0
	s_barrier
	s_add_i32 s0, s0, s61
	v_lshl_add_u64 v[210:211], v[210:211], 0, s[76:77]
	s_mov_b32 m0, s0
	ds_read_b128 v[162:165], v239 offset:49152
	ds_read_b128 v[166:169], v239 offset:50176
	ds_read_b128 v[170:173], v239 offset:51200
	ds_read_b128 v[174:177], v239 offset:52224
	ds_read_b128 v[178:181], v239 offset:53248
	ds_read_b128 v[198:201], v239 offset:54272
	ds_read_b128 v[202:205], v239 offset:55296
	ds_read_b128 v[206:209], v239 offset:56320
	global_load_lds_dwordx4 v[210:211], off
	v_lshl_add_u64 v[210:211], v[212:213], 0, s[76:77]
	s_add_i32 m0, s0, 0x2000
	s_add_i32 s0, s27, s61
	global_load_lds_dwordx4 v[210:211], off
	v_lshl_add_u64 v[210:211], v[214:215], 0, s[76:77]
	s_mov_b32 m0, s0
	s_nop 0
	global_load_lds_dwordx4 v[210:211], off
	v_lshl_add_u64 v[210:211], v[216:217], 0, s[76:77]
	s_add_i32 m0, s0, 0x2000
	s_nop 0
	global_load_lds_dwordx4 v[210:211], off
	v_lshl_add_u64 v[210:211], v[218:219], 0, s[76:77]
	s_mov_b32 m0, s68
	s_nop 0
	global_load_lds_dwordx4 v[210:211], off
	v_lshl_add_u64 v[210:211], v[230:231], 0, s[76:77]
	s_mov_b32 m0, s69
	s_nop 0
	global_load_lds_dwordx4 v[210:211], off
	s_waitcnt vmcnt(8)
	s_waitcnt lgkmcnt(0)
	s_barrier
	s_setprio 1
	s_waitcnt lgkmcnt(0)
	v_mfma_f32_16x16x32_bf16 v[78:81], v[58:61], v[162:165], v[78:81]
	v_mfma_f32_16x16x32_bf16 v[46:49], v[58:61], v[170:173], v[46:49]
	v_mfma_f32_16x16x32_bf16 v[30:33], v[58:61], v[178:181], v[30:33]
	v_mfma_f32_16x16x32_bf16 v[14:17], v[58:61], v[202:205], v[14:17]
	v_mfma_f32_16x16x32_bf16 v[10:13], v[66:69], v[202:205], v[10:13]
	v_mfma_f32_16x16x32_bf16 v[26:29], v[66:69], v[178:181], v[26:29]
	v_mfma_f32_16x16x32_bf16 v[42:45], v[66:69], v[170:173], v[42:45]
	v_mfma_f32_16x16x32_bf16 v[74:77], v[66:69], v[162:165], v[74:77]
	v_mfma_f32_16x16x32_bf16 v[78:81], v[62:65], v[166:169], v[78:81]
	v_mfma_f32_16x16x32_bf16 v[46:49], v[62:65], v[174:177], v[46:49]
	v_mfma_f32_16x16x32_bf16 v[30:33], v[62:65], v[198:201], v[30:33]
	v_mfma_f32_16x16x32_bf16 v[14:17], v[62:65], v[206:209], v[14:17]
	v_mfma_f32_16x16x32_bf16 v[10:13], v[70:73], v[206:209], v[10:13]
	v_mfma_f32_16x16x32_bf16 v[26:29], v[70:73], v[198:201], v[26:29]
	v_mfma_f32_16x16x32_bf16 v[42:45], v[70:73], v[174:177], v[42:45]
	v_mfma_f32_16x16x32_bf16 v[74:77], v[70:73], v[166:169], v[74:77]
	s_setprio 0
	s_setprio 1
	v_mfma_f32_16x16x32_bf16 v[54:57], v[82:85], v[162:165], v[54:57]
	v_mfma_f32_16x16x32_bf16 v[38:41], v[82:85], v[170:173], v[38:41]
	v_mfma_f32_16x16x32_bf16 v[22:25], v[82:85], v[178:181], v[22:25]
	v_mfma_f32_16x16x32_bf16 v[6:9], v[82:85], v[202:205], v[6:9]
	v_mfma_f32_16x16x32_bf16 v[2:5], v[90:93], v[202:205], v[2:5]
	v_mfma_f32_16x16x32_bf16 v[18:21], v[90:93], v[178:181], v[18:21]
	v_mfma_f32_16x16x32_bf16 v[34:37], v[90:93], v[170:173], v[34:37]
	v_mfma_f32_16x16x32_bf16 v[50:53], v[90:93], v[162:165], v[50:53]
	v_mfma_f32_16x16x32_bf16 v[54:57], v[86:89], v[166:169], v[54:57]
	v_mfma_f32_16x16x32_bf16 v[38:41], v[86:89], v[174:177], v[38:41]
	v_mfma_f32_16x16x32_bf16 v[22:25], v[86:89], v[198:201], v[22:25]
	v_mfma_f32_16x16x32_bf16 v[6:9], v[86:89], v[206:209], v[6:9]
	v_mfma_f32_16x16x32_bf16 v[2:5], v[94:97], v[206:209], v[2:5]
	v_mfma_f32_16x16x32_bf16 v[18:21], v[94:97], v[198:201], v[18:21]
	v_mfma_f32_16x16x32_bf16 v[34:37], v[94:97], v[174:177], v[34:37]
	v_mfma_f32_16x16x32_bf16 v[50:53], v[94:97], v[166:169], v[50:53]
	s_setprio 0
	s_barrier
	s_add_u32 s6, s6, 0x100
	s_addc_u32 s7, s7, 0
	s_add_u32 s21, s21, 0x100
	s_addc_u32 s26, s26, 0
	s_mov_b32 s27, s46
.LBB0_671:
	s_add_i32 s46, s27, 2
	s_add_u32 s0, s6, 0x80
	s_addc_u32 s56, s7, 0
	s_add_i32 vcc_lo, 0, 0x10000
	s_cmp_eq_u32 s72, s27
	s_cselect_b32 s57, s51, s56
	s_cselect_b32 s56, s50, s0
	s_cselect_b32 s59, s53, s26
	s_cselect_b32 s58, s52, s21
	s_add_i32 s0, 0, 0x14000
	v_add_u32_e32 v70, vcc_lo, v237
	v_add_u32_e32 v94, s0, v237
	ds_read_b128 v[58:61], v70
	ds_read_b128 v[62:65], v70 offset:1024
	ds_read_b128 v[66:69], v70 offset:2048
	ds_read_b128 v[70:73], v70 offset:3072
	ds_read_b128 v[82:85], v94
	ds_read_b128 v[86:89], v94 offset:1024
	ds_read_b128 v[90:93], v94 offset:2048
	ds_read_b128 v[94:97], v94 offset:3072
	v_lshl_add_u64 v[210:211], s[6:7], 0, v[194:195]
	s_add_i32 m0, s64, 0xc000
	ds_read_b128 v[162:165], v239
	ds_read_b128 v[166:169], v239 offset:1024
	ds_read_b128 v[170:173], v239 offset:2048
	ds_read_b128 v[174:177], v239 offset:3072
	ds_read_b128 v[178:181], v239 offset:4096
	ds_read_b128 v[198:201], v239 offset:5120
	ds_read_b128 v[202:205], v239 offset:6144
	ds_read_b128 v[206:209], v239 offset:7168
	global_load_lds_dwordx4 v[210:211], off
	v_lshl_add_u64 v[210:211], s[6:7], 0, v[196:197]
	s_add_i32 m0, s64, 0xe000
	s_nop 0
	global_load_lds_dwordx4 v[210:211], off
	s_waitcnt vmcnt(8)
	s_waitcnt lgkmcnt(0)
	s_barrier
	s_setprio 1
	s_waitcnt lgkmcnt(0)
	v_mfma_f32_16x16x32_bf16 v[158:161], v[58:61], v[162:165], v[158:161]
	v_mfma_f32_16x16x32_bf16 v[142:145], v[58:61], v[170:173], v[142:145]
	v_mfma_f32_16x16x32_bf16 v[126:129], v[58:61], v[178:181], v[126:129]
	v_mfma_f32_16x16x32_bf16 v[110:113], v[58:61], v[202:205], v[110:113]
	v_mfma_f32_16x16x32_bf16 v[106:109], v[66:69], v[202:205], v[106:109]
	v_mfma_f32_16x16x32_bf16 v[122:125], v[66:69], v[178:181], v[122:125]
	v_mfma_f32_16x16x32_bf16 v[138:141], v[66:69], v[170:173], v[138:141]
	v_mfma_f32_16x16x32_bf16 v[154:157], v[66:69], v[162:165], v[154:157]
	v_mfma_f32_16x16x32_bf16 v[158:161], v[62:65], v[166:169], v[158:161]
	v_mfma_f32_16x16x32_bf16 v[142:145], v[62:65], v[174:177], v[142:145]
	v_mfma_f32_16x16x32_bf16 v[126:129], v[62:65], v[198:201], v[126:129]
	v_mfma_f32_16x16x32_bf16 v[110:113], v[62:65], v[206:209], v[110:113]
	v_mfma_f32_16x16x32_bf16 v[106:109], v[70:73], v[206:209], v[106:109]
	v_mfma_f32_16x16x32_bf16 v[122:125], v[70:73], v[198:201], v[122:125]
	v_mfma_f32_16x16x32_bf16 v[138:141], v[70:73], v[174:177], v[138:141]
	v_mfma_f32_16x16x32_bf16 v[154:157], v[70:73], v[166:169], v[154:157]
	s_setprio 0
	s_setprio 1
	v_mfma_f32_16x16x32_bf16 v[150:153], v[82:85], v[162:165], v[150:153]
	v_mfma_f32_16x16x32_bf16 v[134:137], v[82:85], v[170:173], v[134:137]
	v_mfma_f32_16x16x32_bf16 v[118:121], v[82:85], v[178:181], v[118:121]
	v_mfma_f32_16x16x32_bf16 v[102:105], v[82:85], v[202:205], v[102:105]
	v_mfma_f32_16x16x32_bf16 v[98:101], v[90:93], v[202:205], v[98:101]
	v_mfma_f32_16x16x32_bf16 v[114:117], v[90:93], v[178:181], v[114:117]
	v_mfma_f32_16x16x32_bf16 v[130:133], v[90:93], v[170:173], v[130:133]
	v_mfma_f32_16x16x32_bf16 v[146:149], v[90:93], v[162:165], v[146:149]
	v_mfma_f32_16x16x32_bf16 v[150:153], v[86:89], v[166:169], v[150:153]
	v_mfma_f32_16x16x32_bf16 v[134:137], v[86:89], v[174:177], v[134:137]
	v_mfma_f32_16x16x32_bf16 v[118:121], v[86:89], v[198:201], v[118:121]
	v_mfma_f32_16x16x32_bf16 v[102:105], v[86:89], v[206:209], v[102:105]
	v_mfma_f32_16x16x32_bf16 v[98:101], v[94:97], v[206:209], v[98:101]
	v_mfma_f32_16x16x32_bf16 v[114:117], v[94:97], v[198:201], v[114:117]
	v_mfma_f32_16x16x32_bf16 v[130:133], v[94:97], v[174:177], v[130:133]
	v_mfma_f32_16x16x32_bf16 v[146:149], v[94:97], v[166:169], v[146:149]
	s_setprio 0
	s_barrier
	s_add_i32 s27, vcc_lo, s61
	v_lshl_add_u64 v[210:211], s[58:59], 0, v[186:187]
	s_mov_b32 m0, s27
	ds_read_b128 v[162:165], v239 offset:16384
	ds_read_b128 v[166:169], v239 offset:17408
	ds_read_b128 v[170:173], v239 offset:18432
	ds_read_b128 v[174:177], v239 offset:19456
	ds_read_b128 v[178:181], v239 offset:20480
	ds_read_b128 v[198:201], v239 offset:21504
	ds_read_b128 v[202:205], v239 offset:22528
	ds_read_b128 v[206:209], v239 offset:23552
	global_load_lds_dwordx4 v[210:211], off
	s_add_i32 m0, s27, 0x2000
	v_lshl_add_u64 v[212:213], s[58:59], 0, v[182:183]
	s_add_u32 s58, s58, s12
	s_addc_u32 s59, s59, 0
	s_add_i32 s0, s0, s61
	global_load_lds_dwordx4 v[212:213], off
	v_lshl_add_u64 v[214:215], s[58:59], 0, v[186:187]
	s_mov_b32 m0, s0
	v_lshl_add_u64 v[216:217], s[58:59], 0, v[182:183]
	global_load_lds_dwordx4 v[214:215], off
	s_add_i32 m0, s0, 0x2000
	v_lshl_add_u64 v[218:219], s[56:57], 0, v[188:189]
	global_load_lds_dwordx4 v[216:217], off
	s_mov_b32 m0, s64
	v_lshl_add_u64 v[230:231], s[56:57], 0, v[184:185]
	global_load_lds_dwordx4 v[218:219], off
	s_mov_b32 m0, s65
	s_nop 0
	global_load_lds_dwordx4 v[230:231], off
	s_waitcnt vmcnt(8)
	s_waitcnt lgkmcnt(0)
	s_barrier
	s_setprio 1
	s_waitcnt lgkmcnt(0)
	v_mfma_f32_16x16x32_bf16 v[78:81], v[58:61], v[162:165], v[78:81]
	v_mfma_f32_16x16x32_bf16 v[46:49], v[58:61], v[170:173], v[46:49]
	v_mfma_f32_16x16x32_bf16 v[30:33], v[58:61], v[178:181], v[30:33]
	v_mfma_f32_16x16x32_bf16 v[14:17], v[58:61], v[202:205], v[14:17]
	v_mfma_f32_16x16x32_bf16 v[10:13], v[66:69], v[202:205], v[10:13]
	v_mfma_f32_16x16x32_bf16 v[26:29], v[66:69], v[178:181], v[26:29]
	v_mfma_f32_16x16x32_bf16 v[42:45], v[66:69], v[170:173], v[42:45]
	v_mfma_f32_16x16x32_bf16 v[74:77], v[66:69], v[162:165], v[74:77]
	v_mfma_f32_16x16x32_bf16 v[78:81], v[62:65], v[166:169], v[78:81]
	v_mfma_f32_16x16x32_bf16 v[46:49], v[62:65], v[174:177], v[46:49]
	v_mfma_f32_16x16x32_bf16 v[30:33], v[62:65], v[198:201], v[30:33]
	v_mfma_f32_16x16x32_bf16 v[14:17], v[62:65], v[206:209], v[14:17]
	v_mfma_f32_16x16x32_bf16 v[10:13], v[70:73], v[206:209], v[10:13]
	v_mfma_f32_16x16x32_bf16 v[26:29], v[70:73], v[198:201], v[26:29]
	v_mfma_f32_16x16x32_bf16 v[42:45], v[70:73], v[174:177], v[42:45]
	v_mfma_f32_16x16x32_bf16 v[74:77], v[70:73], v[166:169], v[74:77]
	s_setprio 0
	s_setprio 1
	v_mfma_f32_16x16x32_bf16 v[54:57], v[82:85], v[162:165], v[54:57]
	v_mfma_f32_16x16x32_bf16 v[38:41], v[82:85], v[170:173], v[38:41]
	v_mfma_f32_16x16x32_bf16 v[22:25], v[82:85], v[178:181], v[22:25]
	v_mfma_f32_16x16x32_bf16 v[6:9], v[82:85], v[202:205], v[6:9]
	v_mfma_f32_16x16x32_bf16 v[2:5], v[90:93], v[202:205], v[2:5]
	v_mfma_f32_16x16x32_bf16 v[18:21], v[90:93], v[178:181], v[18:21]
	v_mfma_f32_16x16x32_bf16 v[34:37], v[90:93], v[170:173], v[34:37]
	v_mfma_f32_16x16x32_bf16 v[50:53], v[90:93], v[162:165], v[50:53]
	v_mfma_f32_16x16x32_bf16 v[54:57], v[86:89], v[166:169], v[54:57]
	v_mfma_f32_16x16x32_bf16 v[38:41], v[86:89], v[174:177], v[38:41]
	v_mfma_f32_16x16x32_bf16 v[22:25], v[86:89], v[198:201], v[22:25]
	v_mfma_f32_16x16x32_bf16 v[6:9], v[86:89], v[206:209], v[6:9]
	v_mfma_f32_16x16x32_bf16 v[2:5], v[94:97], v[206:209], v[2:5]
	v_mfma_f32_16x16x32_bf16 v[18:21], v[94:97], v[198:201], v[18:21]
	v_mfma_f32_16x16x32_bf16 v[34:37], v[94:97], v[174:177], v[34:37]
	v_mfma_f32_16x16x32_bf16 v[50:53], v[94:97], v[166:169], v[50:53]
	s_setprio 0
	s_barrier
	s_add_i32 s0, 0, 0x18000
	s_add_i32 s27, 0, 0x1c000
	v_add_u32_e32 v70, s0, v237
	v_add_u32_e32 v94, s27, v237
	ds_read_b128 v[58:61], v70
	ds_read_b128 v[62:65], v70 offset:1024
	ds_read_b128 v[66:69], v70 offset:2048
	ds_read_b128 v[70:73], v70 offset:3072
	ds_read_b128 v[82:85], v94
	ds_read_b128 v[86:89], v94 offset:1024
	ds_read_b128 v[90:93], v94 offset:2048
	ds_read_b128 v[94:97], v94 offset:3072
	s_add_u32 s56, s56, s12
	s_addc_u32 s57, s57, 0
	s_mov_b32 m0, s66
	v_lshl_add_u64 v[232:233], s[56:57], 0, v[188:189]
	ds_read_b128 v[162:165], v239 offset:32768
	ds_read_b128 v[166:169], v239 offset:33792
	ds_read_b128 v[170:173], v239 offset:34816
	ds_read_b128 v[174:177], v239 offset:35840
	ds_read_b128 v[178:181], v239 offset:36864
	ds_read_b128 v[198:201], v239 offset:37888
	ds_read_b128 v[202:205], v239 offset:38912
	ds_read_b128 v[206:209], v239 offset:39936
	global_load_lds_dwordx4 v[232:233], off
	v_lshl_add_u64 v[232:233], s[56:57], 0, v[184:185]
	s_mov_b32 m0, s67
	s_nop 0
	global_load_lds_dwordx4 v[232:233], off
	s_waitcnt vmcnt(8)
	s_waitcnt lgkmcnt(0)
	s_barrier
	s_setprio 1
	s_waitcnt lgkmcnt(0)
	v_mfma_f32_16x16x32_bf16 v[158:161], v[58:61], v[162:165], v[158:161]
	v_mfma_f32_16x16x32_bf16 v[142:145], v[58:61], v[170:173], v[142:145]
	v_mfma_f32_16x16x32_bf16 v[126:129], v[58:61], v[178:181], v[126:129]
	v_mfma_f32_16x16x32_bf16 v[110:113], v[58:61], v[202:205], v[110:113]
	v_mfma_f32_16x16x32_bf16 v[106:109], v[66:69], v[202:205], v[106:109]
	v_mfma_f32_16x16x32_bf16 v[122:125], v[66:69], v[178:181], v[122:125]
	v_mfma_f32_16x16x32_bf16 v[138:141], v[66:69], v[170:173], v[138:141]
	v_mfma_f32_16x16x32_bf16 v[154:157], v[66:69], v[162:165], v[154:157]
	v_mfma_f32_16x16x32_bf16 v[158:161], v[62:65], v[166:169], v[158:161]
	v_mfma_f32_16x16x32_bf16 v[142:145], v[62:65], v[174:177], v[142:145]
	v_mfma_f32_16x16x32_bf16 v[126:129], v[62:65], v[198:201], v[126:129]
	v_mfma_f32_16x16x32_bf16 v[110:113], v[62:65], v[206:209], v[110:113]
	v_mfma_f32_16x16x32_bf16 v[106:109], v[70:73], v[206:209], v[106:109]
	v_mfma_f32_16x16x32_bf16 v[122:125], v[70:73], v[198:201], v[122:125]
	v_mfma_f32_16x16x32_bf16 v[138:141], v[70:73], v[174:177], v[138:141]
	v_mfma_f32_16x16x32_bf16 v[154:157], v[70:73], v[166:169], v[154:157]
	s_setprio 0
	s_setprio 1
	v_mfma_f32_16x16x32_bf16 v[150:153], v[82:85], v[162:165], v[150:153]
	v_mfma_f32_16x16x32_bf16 v[134:137], v[82:85], v[170:173], v[134:137]
	v_mfma_f32_16x16x32_bf16 v[118:121], v[82:85], v[178:181], v[118:121]
	v_mfma_f32_16x16x32_bf16 v[102:105], v[82:85], v[202:205], v[102:105]
	v_mfma_f32_16x16x32_bf16 v[98:101], v[90:93], v[202:205], v[98:101]
	v_mfma_f32_16x16x32_bf16 v[114:117], v[90:93], v[178:181], v[114:117]
	v_mfma_f32_16x16x32_bf16 v[130:133], v[90:93], v[170:173], v[130:133]
	v_mfma_f32_16x16x32_bf16 v[146:149], v[90:93], v[162:165], v[146:149]
	v_mfma_f32_16x16x32_bf16 v[150:153], v[86:89], v[166:169], v[150:153]
	v_mfma_f32_16x16x32_bf16 v[134:137], v[86:89], v[174:177], v[134:137]
	v_mfma_f32_16x16x32_bf16 v[118:121], v[86:89], v[198:201], v[118:121]
	v_mfma_f32_16x16x32_bf16 v[102:105], v[86:89], v[206:209], v[102:105]
	v_mfma_f32_16x16x32_bf16 v[98:101], v[94:97], v[206:209], v[98:101]
	v_mfma_f32_16x16x32_bf16 v[114:117], v[94:97], v[198:201], v[114:117]
	v_mfma_f32_16x16x32_bf16 v[130:133], v[94:97], v[174:177], v[130:133]
	v_mfma_f32_16x16x32_bf16 v[146:149], v[94:97], v[166:169], v[146:149]
	s_setprio 0
	s_barrier
	s_add_i32 s0, s0, s61
	v_lshl_add_u64 v[210:211], v[210:211], 0, s[76:77]
	s_mov_b32 m0, s0
	ds_read_b128 v[162:165], v239 offset:49152
	ds_read_b128 v[166:169], v239 offset:50176
	ds_read_b128 v[170:173], v239 offset:51200
	ds_read_b128 v[174:177], v239 offset:52224
	ds_read_b128 v[178:181], v239 offset:53248
	ds_read_b128 v[198:201], v239 offset:54272
	ds_read_b128 v[202:205], v239 offset:55296
	ds_read_b128 v[206:209], v239 offset:56320
	global_load_lds_dwordx4 v[210:211], off
	v_lshl_add_u64 v[210:211], v[212:213], 0, s[76:77]
	s_add_i32 m0, s0, 0x2000
	s_add_i32 s0, s27, s61
	global_load_lds_dwordx4 v[210:211], off
	v_lshl_add_u64 v[210:211], v[214:215], 0, s[76:77]
	s_mov_b32 m0, s0
	s_nop 0
	global_load_lds_dwordx4 v[210:211], off
	v_lshl_add_u64 v[210:211], v[216:217], 0, s[76:77]
	s_add_i32 m0, s0, 0x2000
	s_nop 0
	global_load_lds_dwordx4 v[210:211], off
	v_lshl_add_u64 v[210:211], v[218:219], 0, s[76:77]
	s_mov_b32 m0, s68
	s_nop 0
	global_load_lds_dwordx4 v[210:211], off
	v_lshl_add_u64 v[210:211], v[230:231], 0, s[76:77]
	s_mov_b32 m0, s69
	s_nop 0
	global_load_lds_dwordx4 v[210:211], off
	s_waitcnt vmcnt(8)
	s_waitcnt lgkmcnt(0)
	s_barrier
	s_setprio 1
	s_waitcnt lgkmcnt(0)
	v_mfma_f32_16x16x32_bf16 v[78:81], v[58:61], v[162:165], v[78:81]
	v_mfma_f32_16x16x32_bf16 v[46:49], v[58:61], v[170:173], v[46:49]
	v_mfma_f32_16x16x32_bf16 v[30:33], v[58:61], v[178:181], v[30:33]
	v_mfma_f32_16x16x32_bf16 v[14:17], v[58:61], v[202:205], v[14:17]
	v_mfma_f32_16x16x32_bf16 v[10:13], v[66:69], v[202:205], v[10:13]
	v_mfma_f32_16x16x32_bf16 v[26:29], v[66:69], v[178:181], v[26:29]
	v_mfma_f32_16x16x32_bf16 v[42:45], v[66:69], v[170:173], v[42:45]
	v_mfma_f32_16x16x32_bf16 v[74:77], v[66:69], v[162:165], v[74:77]
	v_mfma_f32_16x16x32_bf16 v[78:81], v[62:65], v[166:169], v[78:81]
	v_mfma_f32_16x16x32_bf16 v[46:49], v[62:65], v[174:177], v[46:49]
	v_mfma_f32_16x16x32_bf16 v[30:33], v[62:65], v[198:201], v[30:33]
	v_mfma_f32_16x16x32_bf16 v[14:17], v[62:65], v[206:209], v[14:17]
	v_mfma_f32_16x16x32_bf16 v[10:13], v[70:73], v[206:209], v[10:13]
	v_mfma_f32_16x16x32_bf16 v[26:29], v[70:73], v[198:201], v[26:29]
	v_mfma_f32_16x16x32_bf16 v[42:45], v[70:73], v[174:177], v[42:45]
	v_mfma_f32_16x16x32_bf16 v[74:77], v[70:73], v[166:169], v[74:77]
	s_setprio 0
	s_setprio 1
	v_mfma_f32_16x16x32_bf16 v[54:57], v[82:85], v[162:165], v[54:57]
	v_mfma_f32_16x16x32_bf16 v[38:41], v[82:85], v[170:173], v[38:41]
	v_mfma_f32_16x16x32_bf16 v[22:25], v[82:85], v[178:181], v[22:25]
	v_mfma_f32_16x16x32_bf16 v[6:9], v[82:85], v[202:205], v[6:9]
	v_mfma_f32_16x16x32_bf16 v[2:5], v[90:93], v[202:205], v[2:5]
	v_mfma_f32_16x16x32_bf16 v[18:21], v[90:93], v[178:181], v[18:21]
	v_mfma_f32_16x16x32_bf16 v[34:37], v[90:93], v[170:173], v[34:37]
	v_mfma_f32_16x16x32_bf16 v[50:53], v[90:93], v[162:165], v[50:53]
	v_mfma_f32_16x16x32_bf16 v[54:57], v[86:89], v[166:169], v[54:57]
	v_mfma_f32_16x16x32_bf16 v[38:41], v[86:89], v[174:177], v[38:41]
	v_mfma_f32_16x16x32_bf16 v[22:25], v[86:89], v[198:201], v[22:25]
	v_mfma_f32_16x16x32_bf16 v[6:9], v[86:89], v[206:209], v[6:9]
	v_mfma_f32_16x16x32_bf16 v[2:5], v[94:97], v[206:209], v[2:5]
	v_mfma_f32_16x16x32_bf16 v[18:21], v[94:97], v[198:201], v[18:21]
	v_mfma_f32_16x16x32_bf16 v[34:37], v[94:97], v[174:177], v[34:37]
	v_mfma_f32_16x16x32_bf16 v[50:53], v[94:97], v[166:169], v[50:53]
	s_setprio 0
	s_barrier
	s_add_u32 s6, s6, 0x100
	s_addc_u32 s7, s7, 0
	s_add_u32 s21, s21, 0x100
	s_addc_u32 s26, s26, 0
	s_cmp_ge_u32 s46, s36
	s_mov_b32 s27, s46
	s_cbranch_scc0 .LBB0_671
	s_and_b64 vcc, exec, s[30:31]
	s_cbranch_vccz .LBB0_674
	s_barrier
